# nt hint also on the one-shot residual / norm loads of phases 7, 11, 15, 16, 19
# baseline (speedup 1.0000x reference)
; __device__ __forceinline__ void store8(bf16_t* p, const f32x4& a, const f32x4& b) { u32x4 w; w.x = pk2(a[0], a[1]); w.y = pk2(a[2], a[3]); w.z = pk2(b[0], b[1]); w.w = pk2(b[2], b[3]); *(u32x4*)p = w; }
;     __device__ __forceinline__ void operator()(const f32x4 (&acc)[2][2][4][2], const pg8::Unit& u, int wr, int wc, int fr, int fq, int buf) const {
;     ...
;             const float* hi_ = lat ? hin_l + ((size_t)bb * NLAT + (jt - 1) * 256) * DMODEL : hin_c + (size_t)bb * NCTX * DMODEL;
;             bf16_t* HB = (bf16_t*)(ws + WS_HB) + (size_t)u.pm * 256 * DMODEL; const bool first = hin_l != nullptr;
;             const float* gt = gate + (size_t)(lat ? bb : 16) * 6144;
; #pragma unroll
;             for (int bj = 0; bj < 2; ++bj) {
;                 const int c0 = u.pn * 256 + bj * 128 + wc * 32 + 8 * fq; const f32x4 g0 = *(const f32x4*)(gt + c0), g1 = *(const f32x4*)(gt + c0 + 4);
;                 if (first) { f32x4 h0[8], h1[8];
; #pragma unroll
;                     for (int q = 0; q < 8; ++q) { const size_t off = (size_t)((q >> 2) * 128 + (q & 3) * 16 + rloc0) * DMODEL + c0; h0[q] = *(const f32x4*)(hi_ + off); h1[q] = *(const f32x4*)(hi_ + off + 4); }
;                     __builtin_amdgcn_sched_barrier(0);
; #pragma unroll
;                     for (int q = 0; q < 8; ++q) { const size_t off = (size_t)((q >> 2) * 128 + (q & 3) * 16 + rloc0) * DMODEL + c0;
;                         store8(HB + off, h0[q] + g0 * acc[q >> 2][bj][q & 3][0], h1[q] + g1 * acc[q >> 2][bj][q & 3][1]); }
.LBB0_1023:
	s_ashr_i32 s5, s4, 31
	s_lshl_b64 s[4:5], s[4:5], 19
	s_add_u32 s60, s46, s4
	s_addc_u32 s61, s47, s5
	s_lshl_b64 s[4:5], s[62:63], 2
	s_add_u32 s4, s39, s4
	s_addc_u32 s5, s40, s5
	s_lshl_b32 s15, s51, 8
	s_or_b32 s15, s15, s42
	v_lshl_add_u32 v170, v130, 3, s15
	v_ashrrev_i32_e32 v171, 31, v170
	v_lshl_add_u64 v[172:173], v[170:171], 2, s[4:5]
	global_load_dwordx4 v[130:133], v[172:173], off offset:16 nt
	global_load_dwordx4 v[134:137], v[172:173], off nt
	v_add_u32_e32 v168, s41, v154
	v_cndmask_b32_e64 v154, 0, 1, s[12:13]
	v_ashrrev_i32_e32 v169, 31, v168
	v_cmp_ne_u32_e64 s[4:5], 1, v154
	v_add_u32_e32 v166, 16, v168
	v_add_u32_e32 v164, 32, v168
	v_add_u32_e32 v162, 48, v168
	v_add_u32_e32 v160, 0x80, v168
	v_add_u32_e32 v158, 0x90, v168
	v_add_u32_e32 v156, 0xa0, v168
	v_add_u32_e32 v154, 0xb0, v168
	s_andn2_b64 vcc, exec, s[12:13]
	v_lshlrev_b64 v[174:175], 12, v[168:169]
	v_lshlrev_b64 v[168:169], 11, v[168:169]
	v_ashrrev_i32_e32 v167, 31, v166
	v_ashrrev_i32_e32 v165, 31, v164
	v_ashrrev_i32_e32 v163, 31, v162
	v_ashrrev_i32_e32 v161, 31, v160
	v_ashrrev_i32_e32 v159, 31, v158
	v_ashrrev_i32_e32 v157, 31, v156
	v_ashrrev_i32_e32 v155, 31, v154
	v_lshl_add_u64 v[176:177], v[170:171], 1, s[60:61]
	s_cbranch_vccnz .LBB0_1033
	v_lshl_add_u64 v[224:225], v[170:171], 2, s[58:59]
	v_lshlrev_b64 v[192:193], 12, v[166:167]
	v_lshlrev_b64 v[200:201], 12, v[164:165]
	v_lshlrev_b64 v[208:209], 12, v[162:163]
	v_lshlrev_b64 v[216:217], 12, v[160:161]
	v_lshlrev_b64 v[226:227], 12, v[158:159]
	v_lshlrev_b64 v[234:235], 12, v[156:157]
	v_lshlrev_b64 v[242:243], 12, v[154:155]
	v_lshl_add_u64 v[188:189], v[224:225], 0, v[174:175]
	v_lshl_add_u64 v[196:197], v[224:225], 0, v[192:193]
	v_lshl_add_u64 v[204:205], v[224:225], 0, v[200:201]
	v_lshl_add_u64 v[212:213], v[224:225], 0, v[208:209]
	v_lshl_add_u64 v[220:221], v[224:225], 0, v[216:217]
	v_lshl_add_u64 v[230:231], v[224:225], 0, v[226:227]
	v_lshl_add_u64 v[238:239], v[224:225], 0, v[234:235]
	v_lshl_add_u64 v[224:225], v[224:225], 0, v[242:243]
	global_load_dwordx4 v[184:187], v[188:189], off offset:16 nt
	s_nop 0
	global_load_dwordx4 v[188:191], v[188:189], off nt
	s_nop 0
	global_load_dwordx4 v[192:195], v[196:197], off offset:16 nt
	s_nop 0
	global_load_dwordx4 v[196:199], v[196:197], off nt
	s_nop 0
	global_load_dwordx4 v[200:203], v[204:205], off offset:16 nt
	s_nop 0
	global_load_dwordx4 v[204:207], v[204:205], off nt
	s_nop 0
	global_load_dwordx4 v[208:211], v[212:213], off offset:16 nt
	s_nop 0
	global_load_dwordx4 v[212:215], v[212:213], off nt
	s_nop 0
	global_load_dwordx4 v[216:219], v[220:221], off offset:16 nt
	s_nop 0
	global_load_dwordx4 v[220:223], v[220:221], off nt
	s_nop 0
	global_load_dwordx4 v[226:229], v[230:231], off offset:16 nt
	s_nop 0
	global_load_dwordx4 v[230:233], v[230:231], off nt
	s_nop 0
	global_load_dwordx4 v[234:237], v[238:239], off offset:16 nt
	s_nop 0
	global_load_dwordx4 v[238:241], v[238:239], off nt
	s_nop 0
	global_load_dwordx4 v[242:245], v[224:225], off offset:16 nt
	global_load_dwordx4 v[246:249], v[224:225], off nt
	s_waitcnt vmcnt(0)
	v_pk_fma_f32 v[190:191], v[128:129], v[136:137], v[190:191]
	v_pk_fma_f32 v[188:189], v[126:127], v[134:135], v[188:189]
	v_pk_fma_f32 v[250:251], v[124:125], v[132:133], v[186:187]
	v_pk_fma_f32 v[186:187], v[122:123], v[130:131], v[184:185]
	v_lshl_add_u64 v[224:225], v[176:177], 0, v[168:169]
	v_cvt_pk_bf16_f32 v184, v188, v189
	v_cvt_pk_bf16_f32 v185, v190, v191
	v_cvt_pk_bf16_f32 v186, v186, v187
	v_cvt_pk_bf16_f32 v187, v250, v251
	global_store_dwordx4 v[224:225], v[184:187], off
	v_pk_fma_f32 v[190:191], v[116:117], v[132:133], v[194:195]
	v_pk_fma_f32 v[192:193], v[114:115], v[130:131], v[192:193]
	v_lshlrev_b64 v[184:185], 11, v[166:167]
	v_lshl_add_u64 v[188:189], v[176:177], 0, v[184:185]
	v_pk_fma_f32 v[186:187], v[120:121], v[136:137], v[198:199]
	v_pk_fma_f32 v[184:185], v[118:119], v[134:135], v[196:197]
	s_nop 0
	v_cvt_pk_bf16_f32 v184, v184, v185
	v_cvt_pk_bf16_f32 v185, v186, v187
	v_cvt_pk_bf16_f32 v186, v192, v193
	v_cvt_pk_bf16_f32 v187, v190, v191
	global_store_dwordx4 v[188:189], v[184:187], off
	v_pk_fma_f32 v[190:191], v[108:109], v[132:133], v[202:203]
	v_pk_fma_f32 v[192:193], v[106:107], v[130:131], v[200:201]
	v_lshlrev_b64 v[184:185], 11, v[164:165]
	v_lshl_add_u64 v[188:189], v[176:177], 0, v[184:185]
	v_pk_fma_f32 v[186:187], v[112:113], v[136:137], v[206:207]
	v_pk_fma_f32 v[184:185], v[110:111], v[134:135], v[204:205]
	s_nop 0
	v_cvt_pk_bf16_f32 v184, v184, v185
	v_cvt_pk_bf16_f32 v185, v186, v187
	v_cvt_pk_bf16_f32 v186, v192, v193
	v_cvt_pk_bf16_f32 v187, v190, v191
	global_store_dwordx4 v[188:189], v[184:187], off
	v_pk_fma_f32 v[190:191], v[100:101], v[132:133], v[210:211]
	v_pk_fma_f32 v[192:193], v[98:99], v[130:131], v[208:209]
	v_lshlrev_b64 v[184:185], 11, v[162:163]
	v_lshl_add_u64 v[188:189], v[176:177], 0, v[184:185]
	v_pk_fma_f32 v[186:187], v[104:105], v[136:137], v[214:215]
	v_pk_fma_f32 v[184:185], v[102:103], v[134:135], v[212:213]
	s_nop 0
	v_cvt_pk_bf16_f32 v184, v184, v185
	v_cvt_pk_bf16_f32 v185, v186, v187
	v_cvt_pk_bf16_f32 v186, v192, v193
	v_cvt_pk_bf16_f32 v187, v190, v191
	global_store_dwordx4 v[188:189], v[184:187], off
	v_pk_fma_f32 v[190:191], v[92:93], v[132:133], v[218:219]
	v_pk_fma_f32 v[192:193], v[90:91], v[130:131], v[216:217]
	v_lshlrev_b64 v[184:185], 11, v[160:161]
	v_lshl_add_u64 v[188:189], v[176:177], 0, v[184:185]
	v_pk_fma_f32 v[186:187], v[96:97], v[136:137], v[222:223]
	v_pk_fma_f32 v[184:185], v[94:95], v[134:135], v[220:221]
	s_nop 0
	v_cvt_pk_bf16_f32 v184, v184, v185
	v_cvt_pk_bf16_f32 v185, v186, v187
; __device__ __forceinline__ float bflo(unsigned u) { return __uint_as_float(u << 16); }
; __device__ __forceinline__ float bfhi(unsigned u) { return __uint_as_float(u & 0xffff0000u); }
; __device__ __forceinline__ void store8(bf16_t* p, const f32x4& a, const f32x4& b) { u32x4 w; w.x = pk2(a[0], a[1]); w.y = pk2(a[2], a[3]); w.z = pk2(b[0], b[1]); w.w = pk2(b[2], b[3]); *(u32x4*)p = w; }
;     __device__ __forceinline__ void operator()(const f32x4 (&acc)[2][2][4][2], const pg8::Unit& u, int wr, int wc, int fr, int fq, int buf) const {
;     ...
;                     for (int q = 0; q < 8; ++q) { const size_t off = (size_t)((q >> 2) * 128 + (q & 3) * 16 + rloc0) * DMODEL + c0;
;                         store8(HB + off, h0[q] + g0 * acc[q >> 2][bj][q & 3][0], h1[q] + g1 * acc[q >> 2][bj][q & 3][1]); }
;                 } else { u32x4 hw[8];
; #pragma unroll
;                     for (int q = 0; q < 8; ++q) { const size_t off = (size_t)((q >> 2) * 128 + (q & 3) * 16 + rloc0) * DMODEL + c0; hw[q] = *(const u32x4*)(HB + off); }
;                     __builtin_amdgcn_sched_barrier(0);
; #pragma unroll
;                     for (int q = 0; q < 8; ++q) { const size_t off = (size_t)((q >> 2) * 128 + (q & 3) * 16 + rloc0) * DMODEL + c0;
;                         const f32x4 h0 = (f32x4){bflo(hw[q].x), bfhi(hw[q].x), bflo(hw[q].y), bfhi(hw[q].y)}, h1 = (f32x4){bflo(hw[q].z), bfhi(hw[q].z), bflo(hw[q].w), bfhi(hw[q].w)};
;                         store8(HB + off, h0 + g0 * acc[q >> 2][bj][q & 3][0], h1 + g1 * acc[q >> 2][bj][q & 3][1]); }
	v_cvt_pk_bf16_f32 v186, v192, v193
	v_cvt_pk_bf16_f32 v187, v190, v191
	global_store_dwordx4 v[188:189], v[184:187], off
	v_pk_fma_f32 v[190:191], v[84:85], v[132:133], v[228:229]
	v_pk_fma_f32 v[192:193], v[82:83], v[130:131], v[226:227]
	v_lshlrev_b64 v[184:185], 11, v[158:159]
	v_lshl_add_u64 v[188:189], v[176:177], 0, v[184:185]
	v_pk_fma_f32 v[186:187], v[88:89], v[136:137], v[232:233]
	v_pk_fma_f32 v[184:185], v[86:87], v[134:135], v[230:231]
	s_nop 0
	v_cvt_pk_bf16_f32 v184, v184, v185
	v_cvt_pk_bf16_f32 v185, v186, v187
	v_cvt_pk_bf16_f32 v186, v192, v193
	v_cvt_pk_bf16_f32 v187, v190, v191
	global_store_dwordx4 v[188:189], v[184:187], off
	v_pk_fma_f32 v[190:191], v[76:77], v[132:133], v[236:237]
	v_pk_fma_f32 v[192:193], v[74:75], v[130:131], v[234:235]
	v_lshlrev_b64 v[184:185], 11, v[156:157]
	v_lshl_add_u64 v[188:189], v[176:177], 0, v[184:185]
	v_pk_fma_f32 v[186:187], v[80:81], v[136:137], v[240:241]
	v_pk_fma_f32 v[184:185], v[78:79], v[134:135], v[238:239]
	s_nop 0
	v_cvt_pk_bf16_f32 v184, v184, v185
	v_cvt_pk_bf16_f32 v185, v186, v187
	v_cvt_pk_bf16_f32 v186, v192, v193
	v_cvt_pk_bf16_f32 v187, v190, v191
	global_store_dwordx4 v[188:189], v[184:187], off
	v_pk_fma_f32 v[190:191], v[68:69], v[132:133], v[244:245]
	v_pk_fma_f32 v[192:193], v[66:67], v[130:131], v[242:243]
	v_lshlrev_b64 v[184:185], 11, v[154:155]
	v_lshl_add_u64 v[188:189], v[176:177], 0, v[184:185]
	v_pk_fma_f32 v[186:187], v[72:73], v[136:137], v[248:249]
	v_pk_fma_f32 v[184:185], v[70:71], v[134:135], v[246:247]
	s_nop 0
	v_cvt_pk_bf16_f32 v184, v184, v185
	v_cvt_pk_bf16_f32 v185, v186, v187
	v_cvt_pk_bf16_f32 v186, v192, v193
	v_cvt_pk_bf16_f32 v187, v190, v191
	global_store_dwordx4 v[188:189], v[184:187], off
	s_cbranch_execnz .LBB0_1026
.LBB0_1025:
	v_lshlrev_b64 v[192:193], 11, v[164:165]
	v_lshlrev_b64 v[200:201], 11, v[160:161]
	v_lshlrev_b64 v[208:209], 11, v[156:157]
	v_lshl_add_u64 v[216:217], v[176:177], 0, v[168:169]
	v_lshlrev_b64 v[184:185], 11, v[166:167]
	v_lshl_add_u64 v[220:221], v[176:177], 0, v[192:193]
	v_lshlrev_b64 v[192:193], 11, v[162:163]
	v_lshl_add_u64 v[224:225], v[176:177], 0, v[200:201]
	v_lshlrev_b64 v[200:201], 11, v[158:159]
	v_lshl_add_u64 v[228:229], v[176:177], 0, v[208:209]
	v_lshlrev_b64 v[208:209], 11, v[154:155]
	v_lshl_add_u64 v[218:219], v[176:177], 0, v[184:185]
	global_load_dwordx4 v[184:187], v[216:217], off nt
	global_load_dwordx4 v[188:191], v[218:219], off nt
	v_lshl_add_u64 v[222:223], v[176:177], 0, v[192:193]
	global_load_dwordx4 v[192:195], v[220:221], off nt
	global_load_dwordx4 v[196:199], v[222:223], off nt
	v_lshl_add_u64 v[226:227], v[176:177], 0, v[200:201]
	global_load_dwordx4 v[200:203], v[224:225], off nt
	global_load_dwordx4 v[204:207], v[226:227], off nt
	v_lshl_add_u64 v[176:177], v[176:177], 0, v[208:209]
	global_load_dwordx4 v[208:211], v[228:229], off nt
	global_load_dwordx4 v[212:215], v[176:177], off nt
	s_waitcnt vmcnt(0)
	v_lshlrev_b32_e32 v230, 16, v184
	v_and_b32_e32 v231, 0xffff0000, v184
	v_lshlrev_b32_e32 v184, 16, v185
	v_and_b32_e32 v185, 0xffff0000, v185
	v_lshlrev_b32_e32 v232, 16, v186
	v_and_b32_e32 v233, 0xffff0000, v186
	v_lshlrev_b32_e32 v186, 16, v187
	v_and_b32_e32 v187, 0xffff0000, v187
	v_pk_fma_f32 v[128:129], v[128:129], v[136:137], v[184:185]
	v_pk_fma_f32 v[126:127], v[126:127], v[134:135], v[230:231]
	v_pk_fma_f32 v[184:185], v[124:125], v[132:133], v[186:187]
	v_pk_fma_f32 v[124:125], v[122:123], v[130:131], v[232:233]
	v_cvt_pk_bf16_f32 v122, v126, v127
	v_cvt_pk_bf16_f32 v123, v128, v129
	v_cvt_pk_bf16_f32 v124, v124, v125
	v_cvt_pk_bf16_f32 v125, v184, v185
	global_store_dwordx4 v[216:217], v[122:125], off
	v_lshlrev_b32_e32 v126, 16, v190
	v_and_b32_e32 v127, 0xffff0000, v190
	v_lshlrev_b32_e32 v122, 16, v188
	v_and_b32_e32 v123, 0xffff0000, v188
	v_lshlrev_b32_e32 v124, 16, v189
	v_and_b32_e32 v125, 0xffff0000, v189
	v_lshlrev_b32_e32 v128, 16, v191
	v_and_b32_e32 v129, 0xffff0000, v191
	v_pk_fma_f32 v[120:121], v[120:121], v[136:137], v[124:125]
	v_pk_fma_f32 v[118:119], v[118:119], v[134:135], v[122:123]
	v_pk_fma_f32 v[122:123], v[116:117], v[132:133], v[128:129]
	v_pk_fma_f32 v[116:117], v[114:115], v[130:131], v[126:127]
	v_cvt_pk_bf16_f32 v114, v118, v119
	v_cvt_pk_bf16_f32 v115, v120, v121
	v_cvt_pk_bf16_f32 v116, v116, v117
	v_cvt_pk_bf16_f32 v117, v122, v123
	global_store_dwordx4 v[218:219], v[114:117], off
	v_lshlrev_b32_e32 v118, 16, v194
	v_and_b32_e32 v119, 0xffff0000, v194
	v_lshlrev_b32_e32 v114, 16, v192
	v_and_b32_e32 v115, 0xffff0000, v192
	v_lshlrev_b32_e32 v116, 16, v193
	v_and_b32_e32 v117, 0xffff0000, v193
	v_lshlrev_b32_e32 v120, 16, v195
	v_and_b32_e32 v121, 0xffff0000, v195
	v_pk_fma_f32 v[112:113], v[112:113], v[136:137], v[116:117]
	v_pk_fma_f32 v[110:111], v[110:111], v[134:135], v[114:115]
	v_pk_fma_f32 v[114:115], v[108:109], v[132:133], v[120:121]
	v_pk_fma_f32 v[108:109], v[106:107], v[130:131], v[118:119]
	v_cvt_pk_bf16_f32 v106, v110, v111
	v_cvt_pk_bf16_f32 v107, v112, v113
	v_cvt_pk_bf16_f32 v108, v108, v109
	v_cvt_pk_bf16_f32 v109, v114, v115
	global_store_dwordx4 v[220:221], v[106:109], off
	v_lshlrev_b32_e32 v110, 16, v198
	v_and_b32_e32 v111, 0xffff0000, v198
	v_lshlrev_b32_e32 v106, 16, v196
	v_and_b32_e32 v107, 0xffff0000, v196
	v_lshlrev_b32_e32 v108, 16, v197
	v_and_b32_e32 v109, 0xffff0000, v197
	v_lshlrev_b32_e32 v112, 16, v199
	v_and_b32_e32 v113, 0xffff0000, v199
	v_pk_fma_f32 v[104:105], v[104:105], v[136:137], v[108:109]
	v_pk_fma_f32 v[102:103], v[102:103], v[134:135], v[106:107]
	v_pk_fma_f32 v[106:107], v[100:101], v[132:133], v[112:113]
	v_pk_fma_f32 v[100:101], v[98:99], v[130:131], v[110:111]
; __device__ __forceinline__ void store8(bf16_t* p, const f32x4& a, const f32x4& b) { u32x4 w; w.x = pk2(a[0], a[1]); w.y = pk2(a[2], a[3]); w.z = pk2(b[0], b[1]); w.w = pk2(b[2], b[3]); *(u32x4*)p = w; }
;     __device__ __forceinline__ void operator()(const f32x4 (&acc)[2][2][4][2], const pg8::Unit& u, int wr, int wc, int fr, int fq, int buf) const {
;     ...
;             for (int bj = 0; bj < 2; ++bj) {
;                 const int c0 = u.pn * 256 + bj * 128 + wc * 32 + 8 * fq; const f32x4 g0 = *(const f32x4*)(gt + c0), g1 = *(const f32x4*)(gt + c0 + 4);
;                 if (first) { f32x4 h0[8], h1[8];
; #pragma unroll
;                     for (int q = 0; q < 8; ++q) { const size_t off = (size_t)((q >> 2) * 128 + (q & 3) * 16 + rloc0) * DMODEL + c0; h0[q] = *(const f32x4*)(hi_ + off); h1[q] = *(const f32x4*)(hi_ + off + 4); }
;                     __builtin_amdgcn_sched_barrier(0);
; #pragma unroll
;                     for (int q = 0; q < 8; ++q) { const size_t off = (size_t)((q >> 2) * 128 + (q & 3) * 16 + rloc0) * DMODEL + c0;
;                         store8(HB + off, h0[q] + g0 * acc[q >> 2][bj][q & 3][0], h1[q] + g1 * acc[q >> 2][bj][q & 3][1]); }
	v_cvt_pk_bf16_f32 v98, v102, v103
	v_cvt_pk_bf16_f32 v99, v104, v105
	v_cvt_pk_bf16_f32 v100, v100, v101
	v_cvt_pk_bf16_f32 v101, v106, v107
	global_store_dwordx4 v[222:223], v[98:101], off
	v_lshlrev_b32_e32 v102, 16, v202
	v_and_b32_e32 v103, 0xffff0000, v202
	v_lshlrev_b32_e32 v98, 16, v200
	v_and_b32_e32 v99, 0xffff0000, v200
	v_lshlrev_b32_e32 v100, 16, v201
	v_and_b32_e32 v101, 0xffff0000, v201
	v_lshlrev_b32_e32 v104, 16, v203
	v_and_b32_e32 v105, 0xffff0000, v203
	v_pk_fma_f32 v[96:97], v[96:97], v[136:137], v[100:101]
	v_pk_fma_f32 v[94:95], v[94:95], v[134:135], v[98:99]
	v_pk_fma_f32 v[98:99], v[92:93], v[132:133], v[104:105]
	v_pk_fma_f32 v[92:93], v[90:91], v[130:131], v[102:103]
	v_cvt_pk_bf16_f32 v90, v94, v95
	v_cvt_pk_bf16_f32 v91, v96, v97
	v_cvt_pk_bf16_f32 v92, v92, v93
	v_cvt_pk_bf16_f32 v93, v98, v99
	global_store_dwordx4 v[224:225], v[90:93], off
	v_lshlrev_b32_e32 v94, 16, v206
	v_and_b32_e32 v95, 0xffff0000, v206
	v_lshlrev_b32_e32 v90, 16, v204
	v_and_b32_e32 v91, 0xffff0000, v204
	v_lshlrev_b32_e32 v92, 16, v205
	v_and_b32_e32 v93, 0xffff0000, v205
	v_lshlrev_b32_e32 v96, 16, v207
	v_and_b32_e32 v97, 0xffff0000, v207
	v_pk_fma_f32 v[88:89], v[88:89], v[136:137], v[92:93]
	v_pk_fma_f32 v[86:87], v[86:87], v[134:135], v[90:91]
	v_pk_fma_f32 v[90:91], v[84:85], v[132:133], v[96:97]
	v_pk_fma_f32 v[84:85], v[82:83], v[130:131], v[94:95]
	v_cvt_pk_bf16_f32 v82, v86, v87
	v_cvt_pk_bf16_f32 v83, v88, v89
	v_cvt_pk_bf16_f32 v84, v84, v85
	v_cvt_pk_bf16_f32 v85, v90, v91
	global_store_dwordx4 v[226:227], v[82:85], off
	v_lshlrev_b32_e32 v86, 16, v210
	v_and_b32_e32 v87, 0xffff0000, v210
	v_lshlrev_b32_e32 v82, 16, v208
	v_and_b32_e32 v83, 0xffff0000, v208
	v_lshlrev_b32_e32 v84, 16, v209
	v_and_b32_e32 v85, 0xffff0000, v209
	v_lshlrev_b32_e32 v88, 16, v211
	v_and_b32_e32 v89, 0xffff0000, v211
	v_pk_fma_f32 v[80:81], v[80:81], v[136:137], v[84:85]
	v_pk_fma_f32 v[78:79], v[78:79], v[134:135], v[82:83]
	v_pk_fma_f32 v[82:83], v[76:77], v[132:133], v[88:89]
	v_pk_fma_f32 v[76:77], v[74:75], v[130:131], v[86:87]
	v_cvt_pk_bf16_f32 v74, v78, v79
	v_cvt_pk_bf16_f32 v75, v80, v81
	v_cvt_pk_bf16_f32 v76, v76, v77
	v_cvt_pk_bf16_f32 v77, v82, v83
	global_store_dwordx4 v[228:229], v[74:77], off
	v_lshlrev_b32_e32 v78, 16, v214
	v_and_b32_e32 v79, 0xffff0000, v214
	v_lshlrev_b32_e32 v74, 16, v212
	v_and_b32_e32 v75, 0xffff0000, v212
	v_lshlrev_b32_e32 v76, 16, v213
	v_and_b32_e32 v77, 0xffff0000, v213
	v_lshlrev_b32_e32 v80, 16, v215
	v_and_b32_e32 v81, 0xffff0000, v215
	v_pk_fma_f32 v[72:73], v[72:73], v[136:137], v[76:77]
	v_pk_fma_f32 v[70:71], v[70:71], v[134:135], v[74:75]
	v_pk_fma_f32 v[74:75], v[68:69], v[132:133], v[80:81]
	v_pk_fma_f32 v[68:69], v[66:67], v[130:131], v[78:79]
	v_cvt_pk_bf16_f32 v66, v70, v71
	v_cvt_pk_bf16_f32 v67, v72, v73
	v_cvt_pk_bf16_f32 v68, v68, v69
	v_cvt_pk_bf16_f32 v69, v74, v75
	global_store_dwordx4 v[176:177], v[66:69], off
.LBB0_1026:
	global_load_dwordx4 v[66:69], v[172:173], off offset:528 nt
	s_nop 0
	global_load_dwordx4 v[70:73], v[172:173], off offset:512 nt
	v_add_u32_e32 v76, 0x80, v170
	v_ashrrev_i32_e32 v77, 31, v76
	s_and_b64 vcc, exec, s[4:5]
	v_lshl_add_u64 v[74:75], v[76:77], 1, s[60:61]
	s_cbranch_vccnz .LBB0_1034
	s_waitcnt vmcnt(0)
	v_lshl_add_u64 v[132:133], v[76:77], 2, s[58:59]
	v_lshlrev_b64 v[84:85], 12, v[166:167]
	v_lshlrev_b64 v[92:93], 12, v[164:165]
	v_lshlrev_b64 v[100:101], 12, v[162:163]
	v_lshlrev_b64 v[108:109], 12, v[160:161]
	v_lshlrev_b64 v[116:117], 12, v[158:159]
	v_lshlrev_b64 v[124:125], 12, v[156:157]
	v_lshlrev_b64 v[134:135], 12, v[154:155]
	v_lshl_add_u64 v[80:81], v[132:133], 0, v[174:175]
	v_lshl_add_u64 v[88:89], v[132:133], 0, v[84:85]
	v_lshl_add_u64 v[96:97], v[132:133], 0, v[92:93]
	v_lshl_add_u64 v[104:105], v[132:133], 0, v[100:101]
	v_lshl_add_u64 v[112:113], v[132:133], 0, v[108:109]
	v_lshl_add_u64 v[120:121], v[132:133], 0, v[116:117]
	v_lshl_add_u64 v[128:129], v[132:133], 0, v[124:125]
	v_lshl_add_u64 v[136:137], v[132:133], 0, v[134:135]
	global_load_dwordx4 v[76:79], v[80:81], off offset:16 nt
	s_nop 0
	global_load_dwordx4 v[80:83], v[80:81], off nt
	s_nop 0
	global_load_dwordx4 v[84:87], v[88:89], off offset:16 nt
	s_nop 0
	global_load_dwordx4 v[88:91], v[88:89], off nt
	s_nop 0
	global_load_dwordx4 v[92:95], v[96:97], off offset:16 nt
	s_nop 0
	global_load_dwordx4 v[96:99], v[96:97], off nt
	s_nop 0
	global_load_dwordx4 v[100:103], v[104:105], off offset:16 nt
	s_nop 0
	global_load_dwordx4 v[104:107], v[104:105], off nt
	s_nop 0
	global_load_dwordx4 v[108:111], v[112:113], off offset:16 nt
	s_nop 0
	global_load_dwordx4 v[112:115], v[112:113], off nt
	s_nop 0
	global_load_dwordx4 v[116:119], v[120:121], off offset:16 nt
	s_nop 0
	global_load_dwordx4 v[120:123], v[120:121], off nt
	s_nop 0
	global_load_dwordx4 v[124:127], v[128:129], off offset:16 nt
	s_nop 0
	global_load_dwordx4 v[128:131], v[128:129], off nt
	s_nop 0
	global_load_dwordx4 v[132:135], v[136:137], off offset:16 nt
	global_load_dwordx4 v[170:173], v[136:137], off nt
	s_waitcnt vmcnt(14)
	v_pk_fma_f32 v[82:83], v[64:65], v[72:73], v[82:83]
	v_pk_fma_f32 v[80:81], v[62:63], v[70:71], v[80:81]
	v_pk_fma_f32 v[174:175], v[60:61], v[68:69], v[78:79]
	v_pk_fma_f32 v[78:79], v[58:59], v[66:67], v[76:77]
	v_lshl_add_u64 v[136:137], v[74:75], 0, v[168:169]
	v_cvt_pk_bf16_f32 v76, v80, v81
	v_cvt_pk_bf16_f32 v77, v82, v83
	v_cvt_pk_bf16_f32 v78, v78, v79
	v_cvt_pk_bf16_f32 v79, v174, v175
	global_store_dwordx4 v[136:137], v[76:79], off
	s_waitcnt vmcnt(14)
	v_pk_fma_f32 v[82:83], v[52:53], v[68:69], v[86:87]
	v_pk_fma_f32 v[84:85], v[50:51], v[66:67], v[84:85]
	v_lshlrev_b64 v[76:77], 11, v[166:167]
	v_lshl_add_u64 v[80:81], v[74:75], 0, v[76:77]
	s_waitcnt vmcnt(13)
; __device__ __forceinline__ void store8(bf16_t* p, const f32x4& a, const f32x4& b) { u32x4 w; w.x = pk2(a[0], a[1]); w.y = pk2(a[2], a[3]); w.z = pk2(b[0], b[1]); w.w = pk2(b[2], b[3]); *(u32x4*)p = w; }
;     __device__ __forceinline__ void operator()(const f32x4 (&acc)[2][2][4][2], const pg8::Unit& u, int wr, int wc, int fr, int fq, int buf) const {
;     ...
;                     for (int q = 0; q < 8; ++q) { const size_t off = (size_t)((q >> 2) * 128 + (q & 3) * 16 + rloc0) * DMODEL + c0;
;                         store8(HB + off, h0[q] + g0 * acc[q >> 2][bj][q & 3][0], h1[q] + g1 * acc[q >> 2][bj][q & 3][1]); }
	v_pk_fma_f32 v[78:79], v[56:57], v[72:73], v[90:91]
	v_pk_fma_f32 v[76:77], v[54:55], v[70:71], v[88:89]
	s_nop 0
	v_cvt_pk_bf16_f32 v76, v76, v77
	v_cvt_pk_bf16_f32 v77, v78, v79
	v_cvt_pk_bf16_f32 v78, v84, v85
	v_cvt_pk_bf16_f32 v79, v82, v83
	global_store_dwordx4 v[80:81], v[76:79], off
	s_waitcnt vmcnt(13)
	v_pk_fma_f32 v[82:83], v[44:45], v[68:69], v[94:95]
	v_pk_fma_f32 v[84:85], v[42:43], v[66:67], v[92:93]
	v_lshlrev_b64 v[76:77], 11, v[164:165]
	v_lshl_add_u64 v[80:81], v[74:75], 0, v[76:77]
	s_waitcnt vmcnt(12)
	v_pk_fma_f32 v[78:79], v[48:49], v[72:73], v[98:99]
	v_pk_fma_f32 v[76:77], v[46:47], v[70:71], v[96:97]
	s_nop 0
	v_cvt_pk_bf16_f32 v76, v76, v77
	v_cvt_pk_bf16_f32 v77, v78, v79
	v_cvt_pk_bf16_f32 v78, v84, v85
	v_cvt_pk_bf16_f32 v79, v82, v83
	global_store_dwordx4 v[80:81], v[76:79], off
	s_waitcnt vmcnt(12)
	v_pk_fma_f32 v[82:83], v[36:37], v[68:69], v[102:103]
	v_pk_fma_f32 v[84:85], v[34:35], v[66:67], v[100:101]
	v_lshlrev_b64 v[76:77], 11, v[162:163]
	v_lshl_add_u64 v[80:81], v[74:75], 0, v[76:77]
	s_waitcnt vmcnt(11)
	v_pk_fma_f32 v[78:79], v[40:41], v[72:73], v[106:107]
	v_pk_fma_f32 v[76:77], v[38:39], v[70:71], v[104:105]
	s_nop 0
	v_cvt_pk_bf16_f32 v76, v76, v77
	v_cvt_pk_bf16_f32 v77, v78, v79
	v_cvt_pk_bf16_f32 v78, v84, v85
	v_cvt_pk_bf16_f32 v79, v82, v83
	global_store_dwordx4 v[80:81], v[76:79], off
	s_waitcnt vmcnt(11)
	v_pk_fma_f32 v[82:83], v[28:29], v[68:69], v[110:111]
	v_pk_fma_f32 v[84:85], v[26:27], v[66:67], v[108:109]
	v_lshlrev_b64 v[76:77], 11, v[160:161]
	v_lshl_add_u64 v[80:81], v[74:75], 0, v[76:77]
	s_waitcnt vmcnt(10)
	v_pk_fma_f32 v[78:79], v[32:33], v[72:73], v[114:115]
	v_pk_fma_f32 v[76:77], v[30:31], v[70:71], v[112:113]
	s_nop 0
	v_cvt_pk_bf16_f32 v76, v76, v77
	v_cvt_pk_bf16_f32 v77, v78, v79
	v_cvt_pk_bf16_f32 v78, v84, v85
	v_cvt_pk_bf16_f32 v79, v82, v83
	global_store_dwordx4 v[80:81], v[76:79], off
	s_waitcnt vmcnt(10)
	v_pk_fma_f32 v[82:83], v[20:21], v[68:69], v[118:119]
	v_pk_fma_f32 v[84:85], v[18:19], v[66:67], v[116:117]
	v_lshlrev_b64 v[76:77], 11, v[158:159]
	v_lshl_add_u64 v[80:81], v[74:75], 0, v[76:77]
	s_waitcnt vmcnt(9)
	v_pk_fma_f32 v[78:79], v[24:25], v[72:73], v[122:123]
	v_pk_fma_f32 v[76:77], v[22:23], v[70:71], v[120:121]
	s_nop 0
	v_cvt_pk_bf16_f32 v76, v76, v77
	v_cvt_pk_bf16_f32 v77, v78, v79
	v_cvt_pk_bf16_f32 v78, v84, v85
	v_cvt_pk_bf16_f32 v79, v82, v83
	global_store_dwordx4 v[80:81], v[76:79], off
	s_waitcnt vmcnt(9)
	v_pk_fma_f32 v[82:83], v[12:13], v[68:69], v[126:127]
	v_pk_fma_f32 v[84:85], v[10:11], v[66:67], v[124:125]
	v_lshlrev_b64 v[76:77], 11, v[156:157]
	v_lshl_add_u64 v[80:81], v[74:75], 0, v[76:77]
	s_waitcnt vmcnt(8)
	v_pk_fma_f32 v[78:79], v[16:17], v[72:73], v[130:131]
	v_pk_fma_f32 v[76:77], v[14:15], v[70:71], v[128:129]
	s_nop 0
	v_cvt_pk_bf16_f32 v76, v76, v77
	v_cvt_pk_bf16_f32 v77, v78, v79
	v_cvt_pk_bf16_f32 v78, v84, v85
	v_cvt_pk_bf16_f32 v79, v82, v83
	global_store_dwordx4 v[80:81], v[76:79], off
	s_waitcnt vmcnt(8)
	v_pk_fma_f32 v[82:83], v[4:5], v[68:69], v[134:135]
	v_pk_fma_f32 v[84:85], v[2:3], v[66:67], v[132:133]
	v_lshlrev_b64 v[76:77], 11, v[154:155]
	v_lshl_add_u64 v[80:81], v[74:75], 0, v[76:77]
	s_waitcnt vmcnt(7)
	v_pk_fma_f32 v[78:79], v[8:9], v[72:73], v[172:173]
	v_pk_fma_f32 v[76:77], v[6:7], v[70:71], v[170:171]
	s_nop 0
	v_cvt_pk_bf16_f32 v76, v76, v77
	v_cvt_pk_bf16_f32 v77, v78, v79
	v_cvt_pk_bf16_f32 v78, v84, v85
	v_cvt_pk_bf16_f32 v79, v82, v83
	global_store_dwordx4 v[80:81], v[76:79], off
	s_cbranch_execnz .LBB0_1029
; __device__ __forceinline__ float bflo(unsigned u) { return __uint_as_float(u << 16); }
; __device__ __forceinline__ float bfhi(unsigned u) { return __uint_as_float(u & 0xffff0000u); }
; __device__ __forceinline__ void store8(bf16_t* p, const f32x4& a, const f32x4& b) { u32x4 w; w.x = pk2(a[0], a[1]); w.y = pk2(a[2], a[3]); w.z = pk2(b[0], b[1]); w.w = pk2(b[2], b[3]); *(u32x4*)p = w; }
;     __device__ __forceinline__ void operator()(const f32x4 (&acc)[2][2][4][2], const pg8::Unit& u, int wr, int wc, int fr, int fq, int buf) const {
;     ...
;                 } else { u32x4 hw[8];
; #pragma unroll
;                     for (int q = 0; q < 8; ++q) { const size_t off = (size_t)((q >> 2) * 128 + (q & 3) * 16 + rloc0) * DMODEL + c0; hw[q] = *(const u32x4*)(HB + off); }
;                     __builtin_amdgcn_sched_barrier(0);
; #pragma unroll
;                     for (int q = 0; q < 8; ++q) { const size_t off = (size_t)((q >> 2) * 128 + (q & 3) * 16 + rloc0) * DMODEL + c0;
;                         const f32x4 h0 = (f32x4){bflo(hw[q].x), bfhi(hw[q].x), bflo(hw[q].y), bfhi(hw[q].y)}, h1 = (f32x4){bflo(hw[q].z), bfhi(hw[q].z), bflo(hw[q].w), bfhi(hw[q].w)};
;                         store8(HB + off, h0 + g0 * acc[q >> 2][bj][q & 3][0], h1 + g1 * acc[q >> 2][bj][q & 3][1]); }
.LBB0_1028:
	v_lshlrev_b64 v[84:85], 11, v[164:165]
	v_lshlrev_b64 v[92:93], 11, v[160:161]
	v_lshlrev_b64 v[100:101], 11, v[156:157]
	v_lshl_add_u64 v[108:109], v[74:75], 0, v[168:169]
	v_lshlrev_b64 v[76:77], 11, v[166:167]
	v_lshl_add_u64 v[112:113], v[74:75], 0, v[84:85]
	v_lshlrev_b64 v[84:85], 11, v[162:163]
	v_lshl_add_u64 v[116:117], v[74:75], 0, v[92:93]
	v_lshlrev_b64 v[92:93], 11, v[158:159]
	v_lshl_add_u64 v[120:121], v[74:75], 0, v[100:101]
	v_lshlrev_b64 v[100:101], 11, v[154:155]
	v_lshl_add_u64 v[110:111], v[74:75], 0, v[76:77]
	global_load_dwordx4 v[76:79], v[108:109], off nt
	global_load_dwordx4 v[80:83], v[110:111], off nt
	v_lshl_add_u64 v[114:115], v[74:75], 0, v[84:85]
	global_load_dwordx4 v[84:87], v[112:113], off nt
	global_load_dwordx4 v[88:91], v[114:115], off nt
	v_lshl_add_u64 v[118:119], v[74:75], 0, v[92:93]
	global_load_dwordx4 v[92:95], v[116:117], off nt
	global_load_dwordx4 v[96:99], v[118:119], off nt
	v_lshl_add_u64 v[74:75], v[74:75], 0, v[100:101]
	global_load_dwordx4 v[100:103], v[120:121], off nt
	global_load_dwordx4 v[104:107], v[74:75], off nt
	s_waitcnt vmcnt(0)
	v_lshlrev_b32_e32 v122, 16, v76
	v_and_b32_e32 v123, 0xffff0000, v76
	v_lshlrev_b32_e32 v76, 16, v77
	v_and_b32_e32 v77, 0xffff0000, v77
	v_lshlrev_b32_e32 v124, 16, v78
	v_and_b32_e32 v125, 0xffff0000, v78
	v_lshlrev_b32_e32 v78, 16, v79
	v_and_b32_e32 v79, 0xffff0000, v79
	v_pk_fma_f32 v[64:65], v[64:65], v[72:73], v[76:77]
	v_pk_fma_f32 v[62:63], v[62:63], v[70:71], v[122:123]
	v_pk_fma_f32 v[76:77], v[60:61], v[68:69], v[78:79]
	v_pk_fma_f32 v[60:61], v[58:59], v[66:67], v[124:125]
	v_cvt_pk_bf16_f32 v58, v62, v63
	v_cvt_pk_bf16_f32 v59, v64, v65
	v_cvt_pk_bf16_f32 v60, v60, v61
	v_cvt_pk_bf16_f32 v61, v76, v77
	global_store_dwordx4 v[108:109], v[58:61], off
	v_lshlrev_b32_e32 v62, 16, v82
	v_and_b32_e32 v63, 0xffff0000, v82
	v_lshlrev_b32_e32 v58, 16, v80
	v_and_b32_e32 v59, 0xffff0000, v80
	v_lshlrev_b32_e32 v60, 16, v81
	v_and_b32_e32 v61, 0xffff0000, v81
	v_lshlrev_b32_e32 v64, 16, v83
	v_and_b32_e32 v65, 0xffff0000, v83
	v_pk_fma_f32 v[56:57], v[56:57], v[72:73], v[60:61]
	v_pk_fma_f32 v[54:55], v[54:55], v[70:71], v[58:59]
	v_pk_fma_f32 v[58:59], v[52:53], v[68:69], v[64:65]
	v_pk_fma_f32 v[52:53], v[50:51], v[66:67], v[62:63]
	v_cvt_pk_bf16_f32 v50, v54, v55
	v_cvt_pk_bf16_f32 v51, v56, v57
	v_cvt_pk_bf16_f32 v52, v52, v53
	v_cvt_pk_bf16_f32 v53, v58, v59
	global_store_dwordx4 v[110:111], v[50:53], off
	v_lshlrev_b32_e32 v54, 16, v86
	v_and_b32_e32 v55, 0xffff0000, v86
	v_lshlrev_b32_e32 v50, 16, v84
	v_and_b32_e32 v51, 0xffff0000, v84
	v_lshlrev_b32_e32 v52, 16, v85
	v_and_b32_e32 v53, 0xffff0000, v85
	v_lshlrev_b32_e32 v56, 16, v87
	v_and_b32_e32 v57, 0xffff0000, v87
	v_pk_fma_f32 v[48:49], v[48:49], v[72:73], v[52:53]
	v_pk_fma_f32 v[46:47], v[46:47], v[70:71], v[50:51]
	v_pk_fma_f32 v[50:51], v[44:45], v[68:69], v[56:57]
	v_pk_fma_f32 v[44:45], v[42:43], v[66:67], v[54:55]
	v_cvt_pk_bf16_f32 v42, v46, v47
	v_cvt_pk_bf16_f32 v43, v48, v49
	v_cvt_pk_bf16_f32 v44, v44, v45
	v_cvt_pk_bf16_f32 v45, v50, v51
	global_store_dwordx4 v[112:113], v[42:45], off
	v_lshlrev_b32_e32 v46, 16, v90
	v_and_b32_e32 v47, 0xffff0000, v90
	v_lshlrev_b32_e32 v42, 16, v88
	v_and_b32_e32 v43, 0xffff0000, v88
	v_lshlrev_b32_e32 v44, 16, v89
	v_and_b32_e32 v45, 0xffff0000, v89
	v_lshlrev_b32_e32 v48, 16, v91
	v_and_b32_e32 v49, 0xffff0000, v91
	v_pk_fma_f32 v[40:41], v[40:41], v[72:73], v[44:45]
	v_pk_fma_f32 v[38:39], v[38:39], v[70:71], v[42:43]
	v_pk_fma_f32 v[42:43], v[36:37], v[68:69], v[48:49]
	v_pk_fma_f32 v[36:37], v[34:35], v[66:67], v[46:47]
	v_cvt_pk_bf16_f32 v34, v38, v39
	v_cvt_pk_bf16_f32 v35, v40, v41
	v_cvt_pk_bf16_f32 v36, v36, v37
	v_cvt_pk_bf16_f32 v37, v42, v43
	global_store_dwordx4 v[114:115], v[34:37], off
	v_lshlrev_b32_e32 v38, 16, v94
	v_and_b32_e32 v39, 0xffff0000, v94
	v_lshlrev_b32_e32 v34, 16, v92
	v_and_b32_e32 v35, 0xffff0000, v92
	v_lshlrev_b32_e32 v36, 16, v93
	v_and_b32_e32 v37, 0xffff0000, v93
	v_lshlrev_b32_e32 v40, 16, v95
	v_and_b32_e32 v41, 0xffff0000, v95
	v_pk_fma_f32 v[32:33], v[32:33], v[72:73], v[36:37]
	v_pk_fma_f32 v[30:31], v[30:31], v[70:71], v[34:35]
	v_pk_fma_f32 v[34:35], v[28:29], v[68:69], v[40:41]
	v_pk_fma_f32 v[28:29], v[26:27], v[66:67], v[38:39]
	v_cvt_pk_bf16_f32 v26, v30, v31
	v_cvt_pk_bf16_f32 v27, v32, v33
	v_cvt_pk_bf16_f32 v28, v28, v29
	v_cvt_pk_bf16_f32 v29, v34, v35
	global_store_dwordx4 v[116:117], v[26:29], off
	v_lshlrev_b32_e32 v30, 16, v98
	v_and_b32_e32 v31, 0xffff0000, v98
	v_lshlrev_b32_e32 v26, 16, v96
	v_and_b32_e32 v27, 0xffff0000, v96
	v_lshlrev_b32_e32 v28, 16, v97
	v_and_b32_e32 v29, 0xffff0000, v97
	v_lshlrev_b32_e32 v32, 16, v99
	v_and_b32_e32 v33, 0xffff0000, v99
	v_pk_fma_f32 v[24:25], v[24:25], v[72:73], v[28:29]
	v_pk_fma_f32 v[22:23], v[22:23], v[70:71], v[26:27]
	v_pk_fma_f32 v[26:27], v[20:21], v[68:69], v[32:33]
	v_pk_fma_f32 v[20:21], v[18:19], v[66:67], v[30:31]
	v_cvt_pk_bf16_f32 v18, v22, v23
	v_cvt_pk_bf16_f32 v19, v24, v25
	v_cvt_pk_bf16_f32 v20, v20, v21
	v_cvt_pk_bf16_f32 v21, v26, v27
	global_store_dwordx4 v[118:119], v[18:21], off
	v_lshlrev_b32_e32 v22, 16, v102
	v_and_b32_e32 v23, 0xffff0000, v102
	v_lshlrev_b32_e32 v18, 16, v100
	v_and_b32_e32 v19, 0xffff0000, v100
	v_lshlrev_b32_e32 v20, 16, v101
	v_and_b32_e32 v21, 0xffff0000, v101
	v_lshlrev_b32_e32 v24, 16, v103
	v_and_b32_e32 v25, 0xffff0000, v103
	v_pk_fma_f32 v[16:17], v[16:17], v[72:73], v[20:21]
	v_pk_fma_f32 v[14:15], v[14:15], v[70:71], v[18:19]
	v_pk_fma_f32 v[18:19], v[12:13], v[68:69], v[24:25]
	v_pk_fma_f32 v[12:13], v[10:11], v[66:67], v[22:23]
	v_cvt_pk_bf16_f32 v10, v14, v15
	v_cvt_pk_bf16_f32 v11, v16, v17
	v_cvt_pk_bf16_f32 v12, v12, v13
	v_cvt_pk_bf16_f32 v13, v18, v19
	global_store_dwordx4 v[120:121], v[10:13], off
	v_lshlrev_b32_e32 v14, 16, v106
	v_and_b32_e32 v15, 0xffff0000, v106
	v_lshlrev_b32_e32 v10, 16, v104
	v_and_b32_e32 v11, 0xffff0000, v104
	v_lshlrev_b32_e32 v12, 16, v105
	v_and_b32_e32 v13, 0xffff0000, v105
	v_lshlrev_b32_e32 v16, 16, v107
	v_and_b32_e32 v17, 0xffff0000, v107
	v_pk_fma_f32 v[8:9], v[8:9], v[72:73], v[12:13]
	v_pk_fma_f32 v[6:7], v[6:7], v[70:71], v[10:11]
	v_pk_fma_f32 v[10:11], v[4:5], v[68:69], v[16:17]
	v_pk_fma_f32 v[4:5], v[2:3], v[66:67], v[14:15]
	v_cvt_pk_bf16_f32 v2, v6, v7
	v_cvt_pk_bf16_f32 v3, v8, v9
	v_cvt_pk_bf16_f32 v4, v4, v5
	v_cvt_pk_bf16_f32 v5, v10, v11
	global_store_dwordx4 v[74:75], v[2:5], off

; __device__ __forceinline__ float bflo(unsigned u) { return __uint_as_float(u << 16); }
; __device__ __forceinline__ float bfhi(unsigned u) { return __uint_as_float(u & 0xffff0000u); }
; __device__ __forceinline__ void store8(bf16_t* p, const f32x4& a, const f32x4& b) { u32x4 w; w.x = pk2(a[0], a[1]); w.y = pk2(a[2], a[3]); w.z = pk2(b[0], b[1]); w.w = pk2(b[2], b[3]); *(u32x4*)p = w; }
;     __device__ __forceinline__ void operator()(const f32x4 (&acc)[2][2][4][2], const pg8::Unit& u, int wr, int wc, int fr, int fq, int buf) const {
;     ...
;             for (int bj = 0; bj < 2; ++bj) {
;                 const int c0 = u.pn * 256 + bj * 128 + wc * 32 + 8 * fq; const f32x4 g0 = *(const f32x4*)(gt + c0), g1 = *(const f32x4*)(gt + c0 + 4);
;                 if (first) { f32x4 h0[8], h1[8];
; #pragma unroll
;                     for (int q = 0; q < 8; ++q) { const size_t off = (size_t)((q >> 2) * 128 + (q & 3) * 16 + rloc0) * DMODEL + c0; h0[q] = *(const f32x4*)(hi_ + off); h1[q] = *(const f32x4*)(hi_ + off + 4); }
;                     __builtin_amdgcn_sched_barrier(0);
; #pragma unroll
;                     for (int q = 0; q < 8; ++q) { const size_t off = (size_t)((q >> 2) * 128 + (q & 3) * 16 + rloc0) * DMODEL + c0;
;                         store8(HB + off, h0[q] + g0 * acc[q >> 2][bj][q & 3][0], h1[q] + g1 * acc[q >> 2][bj][q & 3][1]); }
;                 } else { u32x4 hw[8];
; #pragma unroll
;                     for (int q = 0; q < 8; ++q) { const size_t off = (size_t)((q >> 2) * 128 + (q & 3) * 16 + rloc0) * DMODEL + c0; hw[q] = *(const u32x4*)(HB + off); }
;                     __builtin_amdgcn_sched_barrier(0);
; #pragma unroll
;                     for (int q = 0; q < 8; ++q) { const size_t off = (size_t)((q >> 2) * 128 + (q & 3) * 16 + rloc0) * DMODEL + c0;
;                         const f32x4 h0 = (f32x4){bflo(hw[q].x), bfhi(hw[q].x), bflo(hw[q].y), bfhi(hw[q].y)}, h1 = (f32x4){bflo(hw[q].z), bfhi(hw[q].z), bflo(hw[q].w), bfhi(hw[q].w)};
;                         store8(HB + off, h0 + g0 * acc[q >> 2][bj][q & 3][0], h1 + g1 * acc[q >> 2][bj][q & 3][1]); }
.LBB0_1415:
	s_ashr_i32 s19, s18, 31
	s_lshl_b64 s[4:5], s[18:19], 19
	s_add_u32 s4, s46, s4
	s_addc_u32 s5, s47, s5
	s_lshl_b64 s[18:19], s[52:53], 2
	s_add_u32 s18, s39, s18
	s_addc_u32 s19, s40, s19
	s_lshl_b32 s13, s60, 8
	v_add_u32_e32 v174, s41, v131
	s_or_b32 s13, s13, s42
	v_lshl_add_u32 v156, v130, 3, s13
	v_ashrrev_i32_e32 v175, 31, v174
	v_add_u32_e32 v162, 32, v174
	v_add_u32_e32 v166, 0x80, v174
	v_add_u32_e32 v172, 0xa0, v174
	v_ashrrev_i32_e32 v157, 31, v156
	v_lshlrev_b64 v[158:159], 11, v[174:175]
	v_add_u32_e32 v160, 16, v174
	v_ashrrev_i32_e32 v163, 31, v162
	v_add_u32_e32 v164, 48, v174
	v_ashrrev_i32_e32 v167, 31, v166
	v_add_u32_e32 v168, 0x90, v174
	v_ashrrev_i32_e32 v173, 31, v172
	v_add_u32_e32 v174, 0xb0, v174
	v_lshl_add_u64 v[176:177], v[156:157], 1, s[4:5]
	v_ashrrev_i32_e32 v161, 31, v160
	v_lshlrev_b64 v[162:163], 11, v[162:163]
	v_ashrrev_i32_e32 v165, 31, v164
	v_lshlrev_b64 v[166:167], 11, v[166:167]
	v_ashrrev_i32_e32 v169, 31, v168
	v_lshlrev_b64 v[172:173], 11, v[172:173]
	v_ashrrev_i32_e32 v175, 31, v174
	v_lshl_add_u64 v[154:155], v[156:157], 2, s[18:19]
	v_lshl_add_u64 v[214:215], v[176:177], 0, v[158:159]
	v_lshlrev_b64 v[160:161], 11, v[160:161]
	v_lshl_add_u64 v[218:219], v[176:177], 0, v[162:163]
	v_lshlrev_b64 v[164:165], 11, v[164:165]
	v_lshl_add_u64 v[222:223], v[176:177], 0, v[166:167]
	v_lshlrev_b64 v[168:169], 11, v[168:169]
	v_lshl_add_u64 v[226:227], v[176:177], 0, v[172:173]
	v_lshlrev_b64 v[174:175], 11, v[174:175]
	global_load_dwordx4 v[130:133], v[154:155], off offset:16 nt
	global_load_dwordx4 v[134:137], v[154:155], off nt
	v_lshl_add_u64 v[216:217], v[176:177], 0, v[160:161]
	global_load_dwordx4 v[182:185], v[214:215], off nt
	global_load_dwordx4 v[186:189], v[216:217], off nt
	v_lshl_add_u64 v[220:221], v[176:177], 0, v[164:165]
	global_load_dwordx4 v[190:193], v[218:219], off nt
	global_load_dwordx4 v[194:197], v[220:221], off nt
	v_lshl_add_u64 v[224:225], v[176:177], 0, v[168:169]
	global_load_dwordx4 v[198:201], v[222:223], off nt
	global_load_dwordx4 v[202:205], v[224:225], off nt
	v_lshl_add_u64 v[176:177], v[176:177], 0, v[174:175]
	global_load_dwordx4 v[206:209], v[226:227], off nt
	global_load_dwordx4 v[210:213], v[176:177], off nt
	s_waitcnt vmcnt(0)
	v_lshlrev_b32_e32 v228, 16, v182
	v_and_b32_e32 v229, 0xffff0000, v182
	v_lshlrev_b32_e32 v182, 16, v183
	v_and_b32_e32 v183, 0xffff0000, v183
	v_lshlrev_b32_e32 v230, 16, v184
	v_and_b32_e32 v231, 0xffff0000, v184
	v_lshlrev_b32_e32 v184, 16, v185
	v_and_b32_e32 v185, 0xffff0000, v185
	v_pk_fma_f32 v[128:129], v[128:129], v[136:137], v[182:183]
	v_pk_fma_f32 v[126:127], v[126:127], v[134:135], v[228:229]
	v_pk_fma_f32 v[182:183], v[124:125], v[132:133], v[184:185]
	v_pk_fma_f32 v[124:125], v[122:123], v[130:131], v[230:231]
	v_cvt_pk_bf16_f32 v122, v126, v127
	v_cvt_pk_bf16_f32 v123, v128, v129
	v_cvt_pk_bf16_f32 v124, v124, v125
	v_cvt_pk_bf16_f32 v125, v182, v183
	global_store_dwordx4 v[214:215], v[122:125], off
	v_lshlrev_b32_e32 v126, 16, v188
	v_and_b32_e32 v127, 0xffff0000, v188
	v_lshlrev_b32_e32 v122, 16, v186
	v_and_b32_e32 v123, 0xffff0000, v186
	v_lshlrev_b32_e32 v124, 16, v187
	v_and_b32_e32 v125, 0xffff0000, v187
	v_lshlrev_b32_e32 v128, 16, v189
	v_and_b32_e32 v129, 0xffff0000, v189
	v_pk_fma_f32 v[120:121], v[120:121], v[136:137], v[124:125]
	v_pk_fma_f32 v[118:119], v[118:119], v[134:135], v[122:123]
	v_pk_fma_f32 v[122:123], v[116:117], v[132:133], v[128:129]
	v_pk_fma_f32 v[116:117], v[114:115], v[130:131], v[126:127]
	v_cvt_pk_bf16_f32 v114, v118, v119
	v_cvt_pk_bf16_f32 v115, v120, v121
	v_cvt_pk_bf16_f32 v116, v116, v117
	v_cvt_pk_bf16_f32 v117, v122, v123
	global_store_dwordx4 v[216:217], v[114:117], off
	v_lshlrev_b32_e32 v118, 16, v192
	v_and_b32_e32 v119, 0xffff0000, v192
	v_lshlrev_b32_e32 v114, 16, v190
	v_and_b32_e32 v115, 0xffff0000, v190
	v_lshlrev_b32_e32 v116, 16, v191
	v_and_b32_e32 v117, 0xffff0000, v191
	v_lshlrev_b32_e32 v120, 16, v193
	v_and_b32_e32 v121, 0xffff0000, v193
	v_pk_fma_f32 v[112:113], v[112:113], v[136:137], v[116:117]
	v_pk_fma_f32 v[110:111], v[110:111], v[134:135], v[114:115]
	v_pk_fma_f32 v[114:115], v[108:109], v[132:133], v[120:121]
	v_pk_fma_f32 v[108:109], v[106:107], v[130:131], v[118:119]
	v_cvt_pk_bf16_f32 v106, v110, v111
	v_cvt_pk_bf16_f32 v107, v112, v113
	v_cvt_pk_bf16_f32 v108, v108, v109
	v_cvt_pk_bf16_f32 v109, v114, v115
	global_store_dwordx4 v[218:219], v[106:109], off
	v_lshlrev_b32_e32 v110, 16, v196
	v_and_b32_e32 v111, 0xffff0000, v196
	v_lshlrev_b32_e32 v106, 16, v194
	v_and_b32_e32 v107, 0xffff0000, v194
	v_lshlrev_b32_e32 v108, 16, v195
	v_and_b32_e32 v109, 0xffff0000, v195
	v_lshlrev_b32_e32 v112, 16, v197
	v_and_b32_e32 v113, 0xffff0000, v197
	v_pk_fma_f32 v[104:105], v[104:105], v[136:137], v[108:109]
	v_pk_fma_f32 v[102:103], v[102:103], v[134:135], v[106:107]
	v_pk_fma_f32 v[106:107], v[100:101], v[132:133], v[112:113]
	v_pk_fma_f32 v[100:101], v[98:99], v[130:131], v[110:111]
	v_cvt_pk_bf16_f32 v98, v102, v103
	v_cvt_pk_bf16_f32 v99, v104, v105
	v_cvt_pk_bf16_f32 v100, v100, v101
	v_cvt_pk_bf16_f32 v101, v106, v107
	global_store_dwordx4 v[220:221], v[98:101], off
	v_lshlrev_b32_e32 v102, 16, v200
	v_and_b32_e32 v103, 0xffff0000, v200
	v_lshlrev_b32_e32 v98, 16, v198
	v_and_b32_e32 v99, 0xffff0000, v198
	v_lshlrev_b32_e32 v100, 16, v199
	v_and_b32_e32 v101, 0xffff0000, v199
	v_lshlrev_b32_e32 v104, 16, v201
	v_and_b32_e32 v105, 0xffff0000, v201
	v_pk_fma_f32 v[96:97], v[96:97], v[136:137], v[100:101]
	v_pk_fma_f32 v[94:95], v[94:95], v[134:135], v[98:99]
	v_pk_fma_f32 v[98:99], v[92:93], v[132:133], v[104:105]
; __device__ __forceinline__ float bflo(unsigned u) { return __uint_as_float(u << 16); }
; __device__ __forceinline__ float bfhi(unsigned u) { return __uint_as_float(u & 0xffff0000u); }
; __device__ __forceinline__ void store8(bf16_t* p, const f32x4& a, const f32x4& b) { u32x4 w; w.x = pk2(a[0], a[1]); w.y = pk2(a[2], a[3]); w.z = pk2(b[0], b[1]); w.w = pk2(b[2], b[3]); *(u32x4*)p = w; }
;     __device__ __forceinline__ void operator()(const f32x4 (&acc)[2][2][4][2], const pg8::Unit& u, int wr, int wc, int fr, int fq, int buf) const {
;     ...
;             for (int bj = 0; bj < 2; ++bj) {
;                 const int c0 = u.pn * 256 + bj * 128 + wc * 32 + 8 * fq; const f32x4 g0 = *(const f32x4*)(gt + c0), g1 = *(const f32x4*)(gt + c0 + 4);
;                 if (first) { f32x4 h0[8], h1[8];
; #pragma unroll
;                     for (int q = 0; q < 8; ++q) { const size_t off = (size_t)((q >> 2) * 128 + (q & 3) * 16 + rloc0) * DMODEL + c0; h0[q] = *(const f32x4*)(hi_ + off); h1[q] = *(const f32x4*)(hi_ + off + 4); }
;                     __builtin_amdgcn_sched_barrier(0);
; #pragma unroll
;                     for (int q = 0; q < 8; ++q) { const size_t off = (size_t)((q >> 2) * 128 + (q & 3) * 16 + rloc0) * DMODEL + c0;
;                         store8(HB + off, h0[q] + g0 * acc[q >> 2][bj][q & 3][0], h1[q] + g1 * acc[q >> 2][bj][q & 3][1]); }
;                 } else { u32x4 hw[8];
; #pragma unroll
;                     for (int q = 0; q < 8; ++q) { const size_t off = (size_t)((q >> 2) * 128 + (q & 3) * 16 + rloc0) * DMODEL + c0; hw[q] = *(const u32x4*)(HB + off); }
;                     __builtin_amdgcn_sched_barrier(0);
; #pragma unroll
;                     for (int q = 0; q < 8; ++q) { const size_t off = (size_t)((q >> 2) * 128 + (q & 3) * 16 + rloc0) * DMODEL + c0;
;                         const f32x4 h0 = (f32x4){bflo(hw[q].x), bfhi(hw[q].x), bflo(hw[q].y), bfhi(hw[q].y)}, h1 = (f32x4){bflo(hw[q].z), bfhi(hw[q].z), bflo(hw[q].w), bfhi(hw[q].w)};
;                         store8(HB + off, h0 + g0 * acc[q >> 2][bj][q & 3][0], h1 + g1 * acc[q >> 2][bj][q & 3][1]); }
	v_pk_fma_f32 v[92:93], v[90:91], v[130:131], v[102:103]
	v_cvt_pk_bf16_f32 v90, v94, v95
	v_cvt_pk_bf16_f32 v91, v96, v97
	v_cvt_pk_bf16_f32 v92, v92, v93
	v_cvt_pk_bf16_f32 v93, v98, v99
	global_store_dwordx4 v[222:223], v[90:93], off
	v_lshlrev_b32_e32 v94, 16, v204
	v_and_b32_e32 v95, 0xffff0000, v204
	v_lshlrev_b32_e32 v90, 16, v202
	v_and_b32_e32 v91, 0xffff0000, v202
	v_lshlrev_b32_e32 v92, 16, v203
	v_and_b32_e32 v93, 0xffff0000, v203
	v_lshlrev_b32_e32 v96, 16, v205
	v_and_b32_e32 v97, 0xffff0000, v205
	v_pk_fma_f32 v[88:89], v[88:89], v[136:137], v[92:93]
	v_pk_fma_f32 v[86:87], v[86:87], v[134:135], v[90:91]
	v_pk_fma_f32 v[90:91], v[84:85], v[132:133], v[96:97]
	v_pk_fma_f32 v[84:85], v[82:83], v[130:131], v[94:95]
	v_cvt_pk_bf16_f32 v82, v86, v87
	v_cvt_pk_bf16_f32 v83, v88, v89
	v_cvt_pk_bf16_f32 v84, v84, v85
	v_cvt_pk_bf16_f32 v85, v90, v91
	global_store_dwordx4 v[224:225], v[82:85], off
	v_lshlrev_b32_e32 v86, 16, v208
	v_and_b32_e32 v87, 0xffff0000, v208
	v_lshlrev_b32_e32 v82, 16, v206
	v_and_b32_e32 v83, 0xffff0000, v206
	v_lshlrev_b32_e32 v84, 16, v207
	v_and_b32_e32 v85, 0xffff0000, v207
	v_lshlrev_b32_e32 v88, 16, v209
	v_and_b32_e32 v89, 0xffff0000, v209
	v_pk_fma_f32 v[80:81], v[80:81], v[136:137], v[84:85]
	v_pk_fma_f32 v[78:79], v[78:79], v[134:135], v[82:83]
	v_pk_fma_f32 v[82:83], v[76:77], v[132:133], v[88:89]
	v_pk_fma_f32 v[76:77], v[74:75], v[130:131], v[86:87]
	v_cvt_pk_bf16_f32 v74, v78, v79
	v_cvt_pk_bf16_f32 v75, v80, v81
	v_cvt_pk_bf16_f32 v76, v76, v77
	v_cvt_pk_bf16_f32 v77, v82, v83
	global_store_dwordx4 v[226:227], v[74:77], off
	v_lshlrev_b32_e32 v78, 16, v212
	v_and_b32_e32 v79, 0xffff0000, v212
	v_lshlrev_b32_e32 v74, 16, v210
	v_and_b32_e32 v75, 0xffff0000, v210
	v_lshlrev_b32_e32 v76, 16, v211
	v_and_b32_e32 v77, 0xffff0000, v211
	v_lshlrev_b32_e32 v80, 16, v213
	v_and_b32_e32 v81, 0xffff0000, v213
	v_pk_fma_f32 v[72:73], v[72:73], v[136:137], v[76:77]
	v_pk_fma_f32 v[70:71], v[70:71], v[134:135], v[74:75]
	v_pk_fma_f32 v[74:75], v[64:65], v[132:133], v[80:81]
	v_pk_fma_f32 v[64:65], v[62:63], v[130:131], v[78:79]
	v_cvt_pk_bf16_f32 v62, v70, v71
	v_cvt_pk_bf16_f32 v63, v72, v73
	v_cvt_pk_bf16_f32 v64, v64, v65
	v_cvt_pk_bf16_f32 v65, v74, v75
	global_store_dwordx4 v[176:177], v[62:65], off
	v_add_u32_e32 v74, 0x80, v156
	v_ashrrev_i32_e32 v75, 31, v74
	v_lshl_add_u64 v[74:75], v[74:75], 1, s[4:5]
	v_lshl_add_u64 v[108:109], v[74:75], 0, v[158:159]
	v_lshl_add_u64 v[112:113], v[74:75], 0, v[162:163]
	v_lshl_add_u64 v[116:117], v[74:75], 0, v[166:167]
	v_lshl_add_u64 v[120:121], v[74:75], 0, v[172:173]
	global_load_dwordx4 v[62:65], v[154:155], off offset:528 nt
	global_load_dwordx4 v[70:73], v[154:155], off offset:512 nt
	v_lshl_add_u64 v[110:111], v[74:75], 0, v[160:161]
	global_load_dwordx4 v[76:79], v[108:109], off nt
	global_load_dwordx4 v[80:83], v[110:111], off nt
	v_lshl_add_u64 v[114:115], v[74:75], 0, v[164:165]
	global_load_dwordx4 v[84:87], v[112:113], off nt
	global_load_dwordx4 v[88:91], v[114:115], off nt
	v_lshl_add_u64 v[118:119], v[74:75], 0, v[168:169]
	global_load_dwordx4 v[92:95], v[116:117], off nt
	global_load_dwordx4 v[96:99], v[118:119], off nt
	v_lshl_add_u64 v[74:75], v[74:75], 0, v[174:175]
	global_load_dwordx4 v[100:103], v[120:121], off nt
	global_load_dwordx4 v[104:107], v[74:75], off nt
	s_waitcnt vmcnt(7)
	v_lshlrev_b32_e32 v122, 16, v76
	v_and_b32_e32 v123, 0xffff0000, v76
	v_lshlrev_b32_e32 v76, 16, v77
	v_and_b32_e32 v77, 0xffff0000, v77
	v_lshlrev_b32_e32 v124, 16, v78
	v_and_b32_e32 v125, 0xffff0000, v78
	v_lshlrev_b32_e32 v78, 16, v79
	v_and_b32_e32 v79, 0xffff0000, v79
	v_pk_fma_f32 v[68:69], v[68:69], v[72:73], v[76:77]
	v_pk_fma_f32 v[66:67], v[66:67], v[70:71], v[122:123]
	v_pk_fma_f32 v[76:77], v[60:61], v[64:65], v[78:79]
	v_pk_fma_f32 v[60:61], v[58:59], v[62:63], v[124:125]
	v_cvt_pk_bf16_f32 v58, v66, v67
	v_cvt_pk_bf16_f32 v59, v68, v69
	v_cvt_pk_bf16_f32 v60, v60, v61
	v_cvt_pk_bf16_f32 v61, v76, v77
	global_store_dwordx4 v[108:109], v[58:61], off
	s_waitcnt vmcnt(7)
	v_lshlrev_b32_e32 v66, 16, v82
	v_and_b32_e32 v67, 0xffff0000, v82
	v_lshlrev_b32_e32 v58, 16, v80
	v_and_b32_e32 v59, 0xffff0000, v80
	v_lshlrev_b32_e32 v60, 16, v81
	v_and_b32_e32 v61, 0xffff0000, v81
	v_lshlrev_b32_e32 v68, 16, v83
	v_and_b32_e32 v69, 0xffff0000, v83
	v_pk_fma_f32 v[56:57], v[56:57], v[72:73], v[60:61]
	v_pk_fma_f32 v[54:55], v[54:55], v[70:71], v[58:59]
	v_pk_fma_f32 v[58:59], v[52:53], v[64:65], v[68:69]
	v_pk_fma_f32 v[52:53], v[50:51], v[62:63], v[66:67]
	v_cvt_pk_bf16_f32 v50, v54, v55
	v_cvt_pk_bf16_f32 v51, v56, v57
	v_cvt_pk_bf16_f32 v52, v52, v53
	v_cvt_pk_bf16_f32 v53, v58, v59
	global_store_dwordx4 v[110:111], v[50:53], off
	s_waitcnt vmcnt(7)
; __device__ __forceinline__ float bflo(unsigned u) { return __uint_as_float(u << 16); }
; __device__ __forceinline__ float bfhi(unsigned u) { return __uint_as_float(u & 0xffff0000u); }
; __device__ __forceinline__ void store8(bf16_t* p, const f32x4& a, const f32x4& b) { u32x4 w; w.x = pk2(a[0], a[1]); w.y = pk2(a[2], a[3]); w.z = pk2(b[0], b[1]); w.w = pk2(b[2], b[3]); *(u32x4*)p = w; }
; #define PG8_BAR __builtin_amdgcn_s_barrier()
; #define PG8_FLAG(v) do { } while (0)
; template <class Epi, class Sched, bool APERM, bool ABLK = false, bool RELAX = true>
; __device__ __forceinline__ void gemm_phase(LAS unsigned char* lds, const Gemm g, const Sched& S, const Epi& E) {
;     ...
;         if (!has_next) break;
;         PG8_FLAG(1u);
; #pragma unroll
;         for (int a = 0; a < 2; ++a)
; #pragma unroll
;             for (int b = 0; b < 2; ++b)
; #pragma unroll
;                 for (int m = 0; m < 4; ++m)
; #pragma unroll
;                     for (int n = 0; n < 2; ++n) acc[a][b][m][n] = (f32x4){0.f, 0.f, 0.f, 0.f};
;         cur = nxt; cA = nA; cB = nB; ++ui;
;         if (wr == 1) PG8_BAR;
;     __device__ __forceinline__ void operator()(const f32x4 (&acc)[2][2][4][2], const pg8::Unit& u, int wr, int wc, int fr, int fq, int buf) const {
;     ...
;                     for (int q = 0; q < 8; ++q) { const size_t off = (size_t)((q >> 2) * 128 + (q & 3) * 16 + rloc0) * DMODEL + c0;
;                         store8(HB + off, h0[q] + g0 * acc[q >> 2][bj][q & 3][0], h1[q] + g1 * acc[q >> 2][bj][q & 3][1]); }
;                 } else { u32x4 hw[8];
; #pragma unroll
;                     for (int q = 0; q < 8; ++q) { const size_t off = (size_t)((q >> 2) * 128 + (q & 3) * 16 + rloc0) * DMODEL + c0; hw[q] = *(const u32x4*)(HB + off); }
;                     __builtin_amdgcn_sched_barrier(0);
; #pragma unroll
;                     for (int q = 0; q < 8; ++q) { const size_t off = (size_t)((q >> 2) * 128 + (q & 3) * 16 + rloc0) * DMODEL + c0;
;                         const f32x4 h0 = (f32x4){bflo(hw[q].x), bfhi(hw[q].x), bflo(hw[q].y), bfhi(hw[q].y)}, h1 = (f32x4){bflo(hw[q].z), bfhi(hw[q].z), bflo(hw[q].w), bfhi(hw[q].w)};
;                         store8(HB + off, h0 + g0 * acc[q >> 2][bj][q & 3][0], h1 + g1 * acc[q >> 2][bj][q & 3][1]); }
	v_lshlrev_b32_e32 v54, 16, v86
	v_and_b32_e32 v55, 0xffff0000, v86
	v_lshlrev_b32_e32 v50, 16, v84
	v_and_b32_e32 v51, 0xffff0000, v84
	v_lshlrev_b32_e32 v52, 16, v85
	v_and_b32_e32 v53, 0xffff0000, v85
	v_lshlrev_b32_e32 v56, 16, v87
	v_and_b32_e32 v57, 0xffff0000, v87
	v_pk_fma_f32 v[48:49], v[48:49], v[72:73], v[52:53]
	v_pk_fma_f32 v[46:47], v[46:47], v[70:71], v[50:51]
	v_pk_fma_f32 v[50:51], v[44:45], v[64:65], v[56:57]
	v_pk_fma_f32 v[44:45], v[42:43], v[62:63], v[54:55]
	v_cvt_pk_bf16_f32 v42, v46, v47
	v_cvt_pk_bf16_f32 v43, v48, v49
	v_cvt_pk_bf16_f32 v44, v44, v45
	v_cvt_pk_bf16_f32 v45, v50, v51
	global_store_dwordx4 v[112:113], v[42:45], off
	s_waitcnt vmcnt(7)
	v_lshlrev_b32_e32 v46, 16, v90
	v_and_b32_e32 v47, 0xffff0000, v90
	v_lshlrev_b32_e32 v42, 16, v88
	v_and_b32_e32 v43, 0xffff0000, v88
	v_lshlrev_b32_e32 v44, 16, v89
	v_and_b32_e32 v45, 0xffff0000, v89
	v_lshlrev_b32_e32 v48, 16, v91
	v_and_b32_e32 v49, 0xffff0000, v91
	v_pk_fma_f32 v[40:41], v[40:41], v[72:73], v[44:45]
	v_pk_fma_f32 v[38:39], v[38:39], v[70:71], v[42:43]
	v_pk_fma_f32 v[42:43], v[36:37], v[64:65], v[48:49]
	v_pk_fma_f32 v[36:37], v[34:35], v[62:63], v[46:47]
	v_cvt_pk_bf16_f32 v34, v38, v39
	v_cvt_pk_bf16_f32 v35, v40, v41
	v_cvt_pk_bf16_f32 v36, v36, v37
	v_cvt_pk_bf16_f32 v37, v42, v43
	global_store_dwordx4 v[114:115], v[34:37], off
	s_waitcnt vmcnt(7)
	v_lshlrev_b32_e32 v38, 16, v94
	v_and_b32_e32 v39, 0xffff0000, v94
	v_lshlrev_b32_e32 v34, 16, v92
	v_and_b32_e32 v35, 0xffff0000, v92
	v_lshlrev_b32_e32 v36, 16, v93
	v_and_b32_e32 v37, 0xffff0000, v93
	v_lshlrev_b32_e32 v40, 16, v95
	v_and_b32_e32 v41, 0xffff0000, v95
	v_pk_fma_f32 v[32:33], v[32:33], v[72:73], v[36:37]
	v_pk_fma_f32 v[30:31], v[30:31], v[70:71], v[34:35]
	v_pk_fma_f32 v[34:35], v[28:29], v[64:65], v[40:41]
	v_pk_fma_f32 v[28:29], v[26:27], v[62:63], v[38:39]
	v_cvt_pk_bf16_f32 v26, v30, v31
	v_cvt_pk_bf16_f32 v27, v32, v33
	v_cvt_pk_bf16_f32 v28, v28, v29
	v_cvt_pk_bf16_f32 v29, v34, v35
	global_store_dwordx4 v[116:117], v[26:29], off
	s_waitcnt vmcnt(7)
	v_lshlrev_b32_e32 v30, 16, v98
	v_and_b32_e32 v31, 0xffff0000, v98
	v_lshlrev_b32_e32 v26, 16, v96
	v_and_b32_e32 v27, 0xffff0000, v96
	v_lshlrev_b32_e32 v28, 16, v97
	v_and_b32_e32 v29, 0xffff0000, v97
	v_lshlrev_b32_e32 v32, 16, v99
	v_and_b32_e32 v33, 0xffff0000, v99
	v_pk_fma_f32 v[24:25], v[24:25], v[72:73], v[28:29]
	v_pk_fma_f32 v[22:23], v[22:23], v[70:71], v[26:27]
	v_pk_fma_f32 v[26:27], v[20:21], v[64:65], v[32:33]
	v_pk_fma_f32 v[20:21], v[18:19], v[62:63], v[30:31]
	v_cvt_pk_bf16_f32 v18, v22, v23
	v_cvt_pk_bf16_f32 v19, v24, v25
	v_cvt_pk_bf16_f32 v20, v20, v21
	v_cvt_pk_bf16_f32 v21, v26, v27
	global_store_dwordx4 v[118:119], v[18:21], off
	s_waitcnt vmcnt(7)
	v_lshlrev_b32_e32 v22, 16, v102
	v_and_b32_e32 v23, 0xffff0000, v102
	v_lshlrev_b32_e32 v18, 16, v100
	v_and_b32_e32 v19, 0xffff0000, v100
	v_lshlrev_b32_e32 v20, 16, v101
	v_and_b32_e32 v21, 0xffff0000, v101
	v_lshlrev_b32_e32 v24, 16, v103
	v_and_b32_e32 v25, 0xffff0000, v103
	v_pk_fma_f32 v[16:17], v[16:17], v[72:73], v[20:21]
	v_pk_fma_f32 v[14:15], v[14:15], v[70:71], v[18:19]
	v_pk_fma_f32 v[18:19], v[12:13], v[64:65], v[24:25]
	v_pk_fma_f32 v[12:13], v[10:11], v[62:63], v[22:23]
	v_cvt_pk_bf16_f32 v10, v14, v15
	v_cvt_pk_bf16_f32 v11, v16, v17
	v_cvt_pk_bf16_f32 v12, v12, v13
	v_cvt_pk_bf16_f32 v13, v18, v19
	global_store_dwordx4 v[120:121], v[10:13], off
	s_waitcnt vmcnt(7)
	v_lshlrev_b32_e32 v14, 16, v106
	v_and_b32_e32 v15, 0xffff0000, v106
	v_lshlrev_b32_e32 v10, 16, v104
	v_and_b32_e32 v11, 0xffff0000, v104
	v_lshlrev_b32_e32 v12, 16, v105
	v_and_b32_e32 v13, 0xffff0000, v105
	v_lshlrev_b32_e32 v16, 16, v107
	v_and_b32_e32 v17, 0xffff0000, v107
	v_pk_fma_f32 v[8:9], v[8:9], v[72:73], v[12:13]
	v_pk_fma_f32 v[6:7], v[6:7], v[70:71], v[10:11]
	v_pk_fma_f32 v[10:11], v[4:5], v[64:65], v[16:17]
	v_pk_fma_f32 v[4:5], v[2:3], v[62:63], v[14:15]
	v_cvt_pk_bf16_f32 v2, v6, v7
	v_cvt_pk_bf16_f32 v3, v8, v9
	v_cvt_pk_bf16_f32 v4, v4, v5
	v_cvt_pk_bf16_f32 v5, v10, v11
	global_store_dwordx4 v[74:75], v[2:5], off
	s_and_b64 vcc, exec, s[0:1]
	s_mov_b64 s[0:1], -1
	s_cbranch_vccnz .LBB0_1399
	s_andn2_b64 vcc, exec, s[6:7]
	s_cbranch_vccnz .LBB0_1398
	s_barrier
	s_branch .LBB0_1398

; __device__ __forceinline__ float bflo(unsigned u) { return __uint_as_float(u << 16); }
; __device__ __forceinline__ float bfhi(unsigned u) { return __uint_as_float(u & 0xffff0000u); }
; __device__ __forceinline__ void store8(bf16_t* p, const f32x4& a, const f32x4& b) { u32x4 w; w.x = pk2(a[0], a[1]); w.y = pk2(a[2], a[3]); w.z = pk2(b[0], b[1]); w.w = pk2(b[2], b[3]); *(u32x4*)p = w; }
;     __device__ __forceinline__ void operator()(const f32x4 (&acc)[2][2][4][2], const pg8::Unit& u, int wr, int wc, int fr, int fq, int buf) const {
;     ...
;             for (int bj = 0; bj < 2; ++bj) {
;                 const int c0 = u.pn * 256 + bj * 128 + wc * 32 + 8 * fq; const f32x4 g0 = *(const f32x4*)(gt + c0), g1 = *(const f32x4*)(gt + c0 + 4);
;                 if (first) { f32x4 h0[8], h1[8];
; #pragma unroll
;                     for (int q = 0; q < 8; ++q) { const size_t off = (size_t)((q >> 2) * 128 + (q & 3) * 16 + rloc0) * DMODEL + c0; h0[q] = *(const f32x4*)(hi_ + off); h1[q] = *(const f32x4*)(hi_ + off + 4); }
;                     __builtin_amdgcn_sched_barrier(0);
; #pragma unroll
;                     for (int q = 0; q < 8; ++q) { const size_t off = (size_t)((q >> 2) * 128 + (q & 3) * 16 + rloc0) * DMODEL + c0;
;                         store8(HB + off, h0[q] + g0 * acc[q >> 2][bj][q & 3][0], h1[q] + g1 * acc[q >> 2][bj][q & 3][1]); }
;                 } else { u32x4 hw[8];
; #pragma unroll
;                     for (int q = 0; q < 8; ++q) { const size_t off = (size_t)((q >> 2) * 128 + (q & 3) * 16 + rloc0) * DMODEL + c0; hw[q] = *(const u32x4*)(HB + off); }
;                     __builtin_amdgcn_sched_barrier(0);
; #pragma unroll
;                     for (int q = 0; q < 8; ++q) { const size_t off = (size_t)((q >> 2) * 128 + (q & 3) * 16 + rloc0) * DMODEL + c0;
;                         const f32x4 h0 = (f32x4){bflo(hw[q].x), bfhi(hw[q].x), bflo(hw[q].y), bfhi(hw[q].y)}, h1 = (f32x4){bflo(hw[q].z), bfhi(hw[q].z), bflo(hw[q].w), bfhi(hw[q].w)};
;                         store8(HB + off, h0 + g0 * acc[q >> 2][bj][q & 3][0], h1 + g1 * acc[q >> 2][bj][q & 3][1]); }
.LBB0_2045:
	s_ashr_i32 s19, s18, 31
	s_lshl_b64 s[18:19], s[18:19], 19
	s_add_u32 s18, s48, s18
	s_addc_u32 s19, s49, s19
	s_lshl_b64 s[20:21], s[20:21], 2
	s_add_u32 s20, s41, s20
	s_addc_u32 s21, s42, s21
	s_lshl_b32 s11, s53, 8
	v_add_u32_e32 v174, s43, v131
	s_or_b32 s11, s11, s44
	v_lshl_add_u32 v156, v130, 3, s11
	v_ashrrev_i32_e32 v175, 31, v174
	v_add_u32_e32 v162, 32, v174
	v_add_u32_e32 v166, 0x80, v174
	v_add_u32_e32 v172, 0xa0, v174
	v_ashrrev_i32_e32 v157, 31, v156
	v_lshlrev_b64 v[158:159], 11, v[174:175]
	v_add_u32_e32 v160, 16, v174
	v_ashrrev_i32_e32 v163, 31, v162
	v_add_u32_e32 v164, 48, v174
	v_ashrrev_i32_e32 v167, 31, v166
	v_add_u32_e32 v168, 0x90, v174
	v_ashrrev_i32_e32 v173, 31, v172
	v_add_u32_e32 v174, 0xb0, v174
	v_lshl_add_u64 v[176:177], v[156:157], 1, s[18:19]
	v_ashrrev_i32_e32 v161, 31, v160
	v_lshlrev_b64 v[162:163], 11, v[162:163]
	v_ashrrev_i32_e32 v165, 31, v164
	v_lshlrev_b64 v[166:167], 11, v[166:167]
	v_ashrrev_i32_e32 v169, 31, v168
	v_lshlrev_b64 v[172:173], 11, v[172:173]
	v_ashrrev_i32_e32 v175, 31, v174
	v_lshl_add_u64 v[154:155], v[156:157], 2, s[20:21]
	v_lshl_add_u64 v[214:215], v[176:177], 0, v[158:159]
	v_lshlrev_b64 v[160:161], 11, v[160:161]
	v_lshl_add_u64 v[218:219], v[176:177], 0, v[162:163]
	v_lshlrev_b64 v[164:165], 11, v[164:165]
	v_lshl_add_u64 v[222:223], v[176:177], 0, v[166:167]
	v_lshlrev_b64 v[168:169], 11, v[168:169]
	v_lshl_add_u64 v[226:227], v[176:177], 0, v[172:173]
	v_lshlrev_b64 v[174:175], 11, v[174:175]
	global_load_dwordx4 v[130:133], v[154:155], off offset:16 nt
	global_load_dwordx4 v[134:137], v[154:155], off nt
	v_lshl_add_u64 v[216:217], v[176:177], 0, v[160:161]
	global_load_dwordx4 v[182:185], v[214:215], off nt
	global_load_dwordx4 v[186:189], v[216:217], off nt
	v_lshl_add_u64 v[220:221], v[176:177], 0, v[164:165]
	global_load_dwordx4 v[190:193], v[218:219], off nt
	global_load_dwordx4 v[194:197], v[220:221], off nt
	v_lshl_add_u64 v[224:225], v[176:177], 0, v[168:169]
	global_load_dwordx4 v[198:201], v[222:223], off nt
	global_load_dwordx4 v[202:205], v[224:225], off nt
	v_lshl_add_u64 v[176:177], v[176:177], 0, v[174:175]
	global_load_dwordx4 v[206:209], v[226:227], off nt
	global_load_dwordx4 v[210:213], v[176:177], off nt
	s_waitcnt vmcnt(0)
	v_lshlrev_b32_e32 v228, 16, v182
	v_and_b32_e32 v229, 0xffff0000, v182
	v_lshlrev_b32_e32 v182, 16, v183
	v_and_b32_e32 v183, 0xffff0000, v183
	v_lshlrev_b32_e32 v230, 16, v184
	v_and_b32_e32 v231, 0xffff0000, v184
	v_lshlrev_b32_e32 v184, 16, v185
	v_and_b32_e32 v185, 0xffff0000, v185
	v_pk_fma_f32 v[128:129], v[128:129], v[136:137], v[182:183]
	v_pk_fma_f32 v[126:127], v[126:127], v[134:135], v[228:229]
	v_pk_fma_f32 v[182:183], v[124:125], v[132:133], v[184:185]
	v_pk_fma_f32 v[124:125], v[122:123], v[130:131], v[230:231]
	v_cvt_pk_bf16_f32 v122, v126, v127
	v_cvt_pk_bf16_f32 v123, v128, v129
	v_cvt_pk_bf16_f32 v124, v124, v125
	v_cvt_pk_bf16_f32 v125, v182, v183
	global_store_dwordx4 v[214:215], v[122:125], off
	v_lshlrev_b32_e32 v126, 16, v188
	v_and_b32_e32 v127, 0xffff0000, v188
	v_lshlrev_b32_e32 v122, 16, v186
	v_and_b32_e32 v123, 0xffff0000, v186
	v_lshlrev_b32_e32 v124, 16, v187
	v_and_b32_e32 v125, 0xffff0000, v187
	v_lshlrev_b32_e32 v128, 16, v189
	v_and_b32_e32 v129, 0xffff0000, v189
	v_pk_fma_f32 v[120:121], v[120:121], v[136:137], v[124:125]
	v_pk_fma_f32 v[118:119], v[118:119], v[134:135], v[122:123]
	v_pk_fma_f32 v[122:123], v[116:117], v[132:133], v[128:129]
	v_pk_fma_f32 v[116:117], v[114:115], v[130:131], v[126:127]
	v_cvt_pk_bf16_f32 v114, v118, v119
	v_cvt_pk_bf16_f32 v115, v120, v121
	v_cvt_pk_bf16_f32 v116, v116, v117
	v_cvt_pk_bf16_f32 v117, v122, v123
	global_store_dwordx4 v[216:217], v[114:117], off
	v_lshlrev_b32_e32 v118, 16, v192
	v_and_b32_e32 v119, 0xffff0000, v192
	v_lshlrev_b32_e32 v114, 16, v190
	v_and_b32_e32 v115, 0xffff0000, v190
	v_lshlrev_b32_e32 v116, 16, v191
	v_and_b32_e32 v117, 0xffff0000, v191
	v_lshlrev_b32_e32 v120, 16, v193
	v_and_b32_e32 v121, 0xffff0000, v193
	v_pk_fma_f32 v[112:113], v[112:113], v[136:137], v[116:117]
	v_pk_fma_f32 v[110:111], v[110:111], v[134:135], v[114:115]
	v_pk_fma_f32 v[114:115], v[108:109], v[132:133], v[120:121]
	v_pk_fma_f32 v[108:109], v[106:107], v[130:131], v[118:119]
	v_cvt_pk_bf16_f32 v106, v110, v111
	v_cvt_pk_bf16_f32 v107, v112, v113
	v_cvt_pk_bf16_f32 v108, v108, v109
	v_cvt_pk_bf16_f32 v109, v114, v115
	global_store_dwordx4 v[218:219], v[106:109], off
	v_lshlrev_b32_e32 v110, 16, v196
	v_and_b32_e32 v111, 0xffff0000, v196
	v_lshlrev_b32_e32 v106, 16, v194
	v_and_b32_e32 v107, 0xffff0000, v194
	v_lshlrev_b32_e32 v108, 16, v195
	v_and_b32_e32 v109, 0xffff0000, v195
	v_lshlrev_b32_e32 v112, 16, v197
	v_and_b32_e32 v113, 0xffff0000, v197
	v_pk_fma_f32 v[104:105], v[104:105], v[136:137], v[108:109]
	v_pk_fma_f32 v[102:103], v[102:103], v[134:135], v[106:107]
	v_pk_fma_f32 v[106:107], v[100:101], v[132:133], v[112:113]
	v_pk_fma_f32 v[100:101], v[98:99], v[130:131], v[110:111]
	v_cvt_pk_bf16_f32 v98, v102, v103
	v_cvt_pk_bf16_f32 v99, v104, v105
	v_cvt_pk_bf16_f32 v100, v100, v101
	v_cvt_pk_bf16_f32 v101, v106, v107
	global_store_dwordx4 v[220:221], v[98:101], off
	v_lshlrev_b32_e32 v102, 16, v200
	v_and_b32_e32 v103, 0xffff0000, v200
	v_lshlrev_b32_e32 v98, 16, v198
	v_and_b32_e32 v99, 0xffff0000, v198
	v_lshlrev_b32_e32 v100, 16, v199
	v_and_b32_e32 v101, 0xffff0000, v199
	v_lshlrev_b32_e32 v104, 16, v201
	v_and_b32_e32 v105, 0xffff0000, v201
	v_pk_fma_f32 v[96:97], v[96:97], v[136:137], v[100:101]
	v_pk_fma_f32 v[94:95], v[94:95], v[134:135], v[98:99]
	v_pk_fma_f32 v[98:99], v[92:93], v[132:133], v[104:105]
; __device__ __forceinline__ float bflo(unsigned u) { return __uint_as_float(u << 16); }
; __device__ __forceinline__ float bfhi(unsigned u) { return __uint_as_float(u & 0xffff0000u); }
; __device__ __forceinline__ void store8(bf16_t* p, const f32x4& a, const f32x4& b) { u32x4 w; w.x = pk2(a[0], a[1]); w.y = pk2(a[2], a[3]); w.z = pk2(b[0], b[1]); w.w = pk2(b[2], b[3]); *(u32x4*)p = w; }
;     __device__ __forceinline__ void operator()(const f32x4 (&acc)[2][2][4][2], const pg8::Unit& u, int wr, int wc, int fr, int fq, int buf) const {
;     ...
;             for (int bj = 0; bj < 2; ++bj) {
;                 const int c0 = u.pn * 256 + bj * 128 + wc * 32 + 8 * fq; const f32x4 g0 = *(const f32x4*)(gt + c0), g1 = *(const f32x4*)(gt + c0 + 4);
;                 if (first) { f32x4 h0[8], h1[8];
; #pragma unroll
;                     for (int q = 0; q < 8; ++q) { const size_t off = (size_t)((q >> 2) * 128 + (q & 3) * 16 + rloc0) * DMODEL + c0; h0[q] = *(const f32x4*)(hi_ + off); h1[q] = *(const f32x4*)(hi_ + off + 4); }
;                     __builtin_amdgcn_sched_barrier(0);
; #pragma unroll
;                     for (int q = 0; q < 8; ++q) { const size_t off = (size_t)((q >> 2) * 128 + (q & 3) * 16 + rloc0) * DMODEL + c0;
;                         store8(HB + off, h0[q] + g0 * acc[q >> 2][bj][q & 3][0], h1[q] + g1 * acc[q >> 2][bj][q & 3][1]); }
;                 } else { u32x4 hw[8];
; #pragma unroll
;                     for (int q = 0; q < 8; ++q) { const size_t off = (size_t)((q >> 2) * 128 + (q & 3) * 16 + rloc0) * DMODEL + c0; hw[q] = *(const u32x4*)(HB + off); }
;                     __builtin_amdgcn_sched_barrier(0);
; #pragma unroll
;                     for (int q = 0; q < 8; ++q) { const size_t off = (size_t)((q >> 2) * 128 + (q & 3) * 16 + rloc0) * DMODEL + c0;
;                         const f32x4 h0 = (f32x4){bflo(hw[q].x), bfhi(hw[q].x), bflo(hw[q].y), bfhi(hw[q].y)}, h1 = (f32x4){bflo(hw[q].z), bfhi(hw[q].z), bflo(hw[q].w), bfhi(hw[q].w)};
;                         store8(HB + off, h0 + g0 * acc[q >> 2][bj][q & 3][0], h1 + g1 * acc[q >> 2][bj][q & 3][1]); }
	v_pk_fma_f32 v[92:93], v[90:91], v[130:131], v[102:103]
	v_cvt_pk_bf16_f32 v90, v94, v95
	v_cvt_pk_bf16_f32 v91, v96, v97
	v_cvt_pk_bf16_f32 v92, v92, v93
	v_cvt_pk_bf16_f32 v93, v98, v99
	global_store_dwordx4 v[222:223], v[90:93], off
	v_lshlrev_b32_e32 v94, 16, v204
	v_and_b32_e32 v95, 0xffff0000, v204
	v_lshlrev_b32_e32 v90, 16, v202
	v_and_b32_e32 v91, 0xffff0000, v202
	v_lshlrev_b32_e32 v92, 16, v203
	v_and_b32_e32 v93, 0xffff0000, v203
	v_lshlrev_b32_e32 v96, 16, v205
	v_and_b32_e32 v97, 0xffff0000, v205
	v_pk_fma_f32 v[88:89], v[88:89], v[136:137], v[92:93]
	v_pk_fma_f32 v[86:87], v[86:87], v[134:135], v[90:91]
	v_pk_fma_f32 v[90:91], v[84:85], v[132:133], v[96:97]
	v_pk_fma_f32 v[84:85], v[82:83], v[130:131], v[94:95]
	v_cvt_pk_bf16_f32 v82, v86, v87
	v_cvt_pk_bf16_f32 v83, v88, v89
	v_cvt_pk_bf16_f32 v84, v84, v85
	v_cvt_pk_bf16_f32 v85, v90, v91
	global_store_dwordx4 v[224:225], v[82:85], off
	v_lshlrev_b32_e32 v86, 16, v208
	v_and_b32_e32 v87, 0xffff0000, v208
	v_lshlrev_b32_e32 v82, 16, v206
	v_and_b32_e32 v83, 0xffff0000, v206
	v_lshlrev_b32_e32 v84, 16, v207
	v_and_b32_e32 v85, 0xffff0000, v207
	v_lshlrev_b32_e32 v88, 16, v209
	v_and_b32_e32 v89, 0xffff0000, v209
	v_pk_fma_f32 v[80:81], v[80:81], v[136:137], v[84:85]
	v_pk_fma_f32 v[78:79], v[78:79], v[134:135], v[82:83]
	v_pk_fma_f32 v[82:83], v[76:77], v[132:133], v[88:89]
	v_pk_fma_f32 v[76:77], v[74:75], v[130:131], v[86:87]
	v_cvt_pk_bf16_f32 v74, v78, v79
	v_cvt_pk_bf16_f32 v75, v80, v81
	v_cvt_pk_bf16_f32 v76, v76, v77
	v_cvt_pk_bf16_f32 v77, v82, v83
	global_store_dwordx4 v[226:227], v[74:77], off
	v_lshlrev_b32_e32 v78, 16, v212
	v_and_b32_e32 v79, 0xffff0000, v212
	v_lshlrev_b32_e32 v74, 16, v210
	v_and_b32_e32 v75, 0xffff0000, v210
	v_lshlrev_b32_e32 v76, 16, v211
	v_and_b32_e32 v77, 0xffff0000, v211
	v_lshlrev_b32_e32 v80, 16, v213
	v_and_b32_e32 v81, 0xffff0000, v213
	v_pk_fma_f32 v[72:73], v[72:73], v[136:137], v[76:77]
	v_pk_fma_f32 v[70:71], v[70:71], v[134:135], v[74:75]
	v_pk_fma_f32 v[74:75], v[64:65], v[132:133], v[80:81]
	v_pk_fma_f32 v[64:65], v[62:63], v[130:131], v[78:79]
	v_cvt_pk_bf16_f32 v62, v70, v71
	v_cvt_pk_bf16_f32 v63, v72, v73
	v_cvt_pk_bf16_f32 v64, v64, v65
	v_cvt_pk_bf16_f32 v65, v74, v75
	global_store_dwordx4 v[176:177], v[62:65], off
	v_add_u32_e32 v74, 0x80, v156
	v_ashrrev_i32_e32 v75, 31, v74
	v_lshl_add_u64 v[74:75], v[74:75], 1, s[18:19]
	v_lshl_add_u64 v[108:109], v[74:75], 0, v[158:159]
	v_lshl_add_u64 v[112:113], v[74:75], 0, v[162:163]
	v_lshl_add_u64 v[116:117], v[74:75], 0, v[166:167]
	v_lshl_add_u64 v[120:121], v[74:75], 0, v[172:173]
	global_load_dwordx4 v[62:65], v[154:155], off offset:528 nt
	global_load_dwordx4 v[70:73], v[154:155], off offset:512 nt
	v_lshl_add_u64 v[110:111], v[74:75], 0, v[160:161]
	global_load_dwordx4 v[76:79], v[108:109], off nt
	global_load_dwordx4 v[80:83], v[110:111], off nt
	v_lshl_add_u64 v[114:115], v[74:75], 0, v[164:165]
	global_load_dwordx4 v[84:87], v[112:113], off nt
	global_load_dwordx4 v[88:91], v[114:115], off nt
	v_lshl_add_u64 v[118:119], v[74:75], 0, v[168:169]
	global_load_dwordx4 v[92:95], v[116:117], off nt
	global_load_dwordx4 v[96:99], v[118:119], off nt
	v_lshl_add_u64 v[74:75], v[74:75], 0, v[174:175]
	global_load_dwordx4 v[100:103], v[120:121], off nt
	global_load_dwordx4 v[104:107], v[74:75], off nt
	s_waitcnt vmcnt(7)
	v_lshlrev_b32_e32 v122, 16, v76
	v_and_b32_e32 v123, 0xffff0000, v76
	v_lshlrev_b32_e32 v76, 16, v77
	v_and_b32_e32 v77, 0xffff0000, v77
	v_lshlrev_b32_e32 v124, 16, v78
	v_and_b32_e32 v125, 0xffff0000, v78
	v_lshlrev_b32_e32 v78, 16, v79
	v_and_b32_e32 v79, 0xffff0000, v79
	v_pk_fma_f32 v[68:69], v[68:69], v[72:73], v[76:77]
	v_pk_fma_f32 v[66:67], v[66:67], v[70:71], v[122:123]
	v_pk_fma_f32 v[76:77], v[60:61], v[64:65], v[78:79]
	v_pk_fma_f32 v[60:61], v[58:59], v[62:63], v[124:125]
	v_cvt_pk_bf16_f32 v58, v66, v67
	v_cvt_pk_bf16_f32 v59, v68, v69
	v_cvt_pk_bf16_f32 v60, v60, v61
	v_cvt_pk_bf16_f32 v61, v76, v77
	global_store_dwordx4 v[108:109], v[58:61], off
	s_waitcnt vmcnt(7)
	v_lshlrev_b32_e32 v66, 16, v82
	v_and_b32_e32 v67, 0xffff0000, v82
	v_lshlrev_b32_e32 v58, 16, v80
	v_and_b32_e32 v59, 0xffff0000, v80
	v_lshlrev_b32_e32 v60, 16, v81
	v_and_b32_e32 v61, 0xffff0000, v81
	v_lshlrev_b32_e32 v68, 16, v83
	v_and_b32_e32 v69, 0xffff0000, v83
	v_pk_fma_f32 v[56:57], v[56:57], v[72:73], v[60:61]
	v_pk_fma_f32 v[54:55], v[54:55], v[70:71], v[58:59]
	v_pk_fma_f32 v[58:59], v[52:53], v[64:65], v[68:69]
	v_pk_fma_f32 v[52:53], v[50:51], v[62:63], v[66:67]
	v_cvt_pk_bf16_f32 v50, v54, v55
	v_cvt_pk_bf16_f32 v51, v56, v57
	v_cvt_pk_bf16_f32 v52, v52, v53
	v_cvt_pk_bf16_f32 v53, v58, v59
	global_store_dwordx4 v[110:111], v[50:53], off
	s_waitcnt vmcnt(7)
; __device__ __forceinline__ float bflo(unsigned u) { return __uint_as_float(u << 16); }
; __device__ __forceinline__ float bfhi(unsigned u) { return __uint_as_float(u & 0xffff0000u); }
; __device__ __forceinline__ void store8(bf16_t* p, const f32x4& a, const f32x4& b) { u32x4 w; w.x = pk2(a[0], a[1]); w.y = pk2(a[2], a[3]); w.z = pk2(b[0], b[1]); w.w = pk2(b[2], b[3]); *(u32x4*)p = w; }
; #define PG8_BAR __builtin_amdgcn_s_barrier()
; #define PG8_FLAG(v) do { } while (0)
; template <class Epi, class Sched, bool APERM, bool ABLK = false, bool RELAX = true>
; __device__ __forceinline__ void gemm_phase(LAS unsigned char* lds, const Gemm g, const Sched& S, const Epi& E) {
;     ...
;         if (!has_next) break;
;         PG8_FLAG(1u);
; #pragma unroll
;         for (int a = 0; a < 2; ++a)
; #pragma unroll
;             for (int b = 0; b < 2; ++b)
; #pragma unroll
;                 for (int m = 0; m < 4; ++m)
; #pragma unroll
;                     for (int n = 0; n < 2; ++n) acc[a][b][m][n] = (f32x4){0.f, 0.f, 0.f, 0.f};
;         cur = nxt; cA = nA; cB = nB; ++ui;
;         if (wr == 1) PG8_BAR;
;     __device__ __forceinline__ void operator()(const f32x4 (&acc)[2][2][4][2], const pg8::Unit& u, int wr, int wc, int fr, int fq, int buf) const {
;     ...
;                     for (int q = 0; q < 8; ++q) { const size_t off = (size_t)((q >> 2) * 128 + (q & 3) * 16 + rloc0) * DMODEL + c0;
;                         store8(HB + off, h0[q] + g0 * acc[q >> 2][bj][q & 3][0], h1[q] + g1 * acc[q >> 2][bj][q & 3][1]); }
;                 } else { u32x4 hw[8];
; #pragma unroll
;                     for (int q = 0; q < 8; ++q) { const size_t off = (size_t)((q >> 2) * 128 + (q & 3) * 16 + rloc0) * DMODEL + c0; hw[q] = *(const u32x4*)(HB + off); }
;                     __builtin_amdgcn_sched_barrier(0);
; #pragma unroll
;                     for (int q = 0; q < 8; ++q) { const size_t off = (size_t)((q >> 2) * 128 + (q & 3) * 16 + rloc0) * DMODEL + c0;
;                         const f32x4 h0 = (f32x4){bflo(hw[q].x), bfhi(hw[q].x), bflo(hw[q].y), bfhi(hw[q].y)}, h1 = (f32x4){bflo(hw[q].z), bfhi(hw[q].z), bflo(hw[q].w), bfhi(hw[q].w)};
;                         store8(HB + off, h0 + g0 * acc[q >> 2][bj][q & 3][0], h1 + g1 * acc[q >> 2][bj][q & 3][1]); }
	v_lshlrev_b32_e32 v54, 16, v86
	v_and_b32_e32 v55, 0xffff0000, v86
	v_lshlrev_b32_e32 v50, 16, v84
	v_and_b32_e32 v51, 0xffff0000, v84
	v_lshlrev_b32_e32 v52, 16, v85
	v_and_b32_e32 v53, 0xffff0000, v85
	v_lshlrev_b32_e32 v56, 16, v87
	v_and_b32_e32 v57, 0xffff0000, v87
	v_pk_fma_f32 v[48:49], v[48:49], v[72:73], v[52:53]
	v_pk_fma_f32 v[46:47], v[46:47], v[70:71], v[50:51]
	v_pk_fma_f32 v[50:51], v[44:45], v[64:65], v[56:57]
	v_pk_fma_f32 v[44:45], v[42:43], v[62:63], v[54:55]
	v_cvt_pk_bf16_f32 v42, v46, v47
	v_cvt_pk_bf16_f32 v43, v48, v49
	v_cvt_pk_bf16_f32 v44, v44, v45
	v_cvt_pk_bf16_f32 v45, v50, v51
	global_store_dwordx4 v[112:113], v[42:45], off
	s_waitcnt vmcnt(7)
	v_lshlrev_b32_e32 v46, 16, v90
	v_and_b32_e32 v47, 0xffff0000, v90
	v_lshlrev_b32_e32 v42, 16, v88
	v_and_b32_e32 v43, 0xffff0000, v88
	v_lshlrev_b32_e32 v44, 16, v89
	v_and_b32_e32 v45, 0xffff0000, v89
	v_lshlrev_b32_e32 v48, 16, v91
	v_and_b32_e32 v49, 0xffff0000, v91
	v_pk_fma_f32 v[40:41], v[40:41], v[72:73], v[44:45]
	v_pk_fma_f32 v[38:39], v[38:39], v[70:71], v[42:43]
	v_pk_fma_f32 v[42:43], v[36:37], v[64:65], v[48:49]
	v_pk_fma_f32 v[36:37], v[34:35], v[62:63], v[46:47]
	v_cvt_pk_bf16_f32 v34, v38, v39
	v_cvt_pk_bf16_f32 v35, v40, v41
	v_cvt_pk_bf16_f32 v36, v36, v37
	v_cvt_pk_bf16_f32 v37, v42, v43
	global_store_dwordx4 v[114:115], v[34:37], off
	s_waitcnt vmcnt(7)
	v_lshlrev_b32_e32 v38, 16, v94
	v_and_b32_e32 v39, 0xffff0000, v94
	v_lshlrev_b32_e32 v34, 16, v92
	v_and_b32_e32 v35, 0xffff0000, v92
	v_lshlrev_b32_e32 v36, 16, v93
	v_and_b32_e32 v37, 0xffff0000, v93
	v_lshlrev_b32_e32 v40, 16, v95
	v_and_b32_e32 v41, 0xffff0000, v95
	v_pk_fma_f32 v[32:33], v[32:33], v[72:73], v[36:37]
	v_pk_fma_f32 v[30:31], v[30:31], v[70:71], v[34:35]
	v_pk_fma_f32 v[34:35], v[28:29], v[64:65], v[40:41]
	v_pk_fma_f32 v[28:29], v[26:27], v[62:63], v[38:39]
	v_cvt_pk_bf16_f32 v26, v30, v31
	v_cvt_pk_bf16_f32 v27, v32, v33
	v_cvt_pk_bf16_f32 v28, v28, v29
	v_cvt_pk_bf16_f32 v29, v34, v35
	global_store_dwordx4 v[116:117], v[26:29], off
	s_waitcnt vmcnt(7)
	v_lshlrev_b32_e32 v30, 16, v98
	v_and_b32_e32 v31, 0xffff0000, v98
	v_lshlrev_b32_e32 v26, 16, v96
	v_and_b32_e32 v27, 0xffff0000, v96
	v_lshlrev_b32_e32 v28, 16, v97
	v_and_b32_e32 v29, 0xffff0000, v97
	v_lshlrev_b32_e32 v32, 16, v99
	v_and_b32_e32 v33, 0xffff0000, v99
	v_pk_fma_f32 v[24:25], v[24:25], v[72:73], v[28:29]
	v_pk_fma_f32 v[22:23], v[22:23], v[70:71], v[26:27]
	v_pk_fma_f32 v[26:27], v[20:21], v[64:65], v[32:33]
	v_pk_fma_f32 v[20:21], v[18:19], v[62:63], v[30:31]
	v_cvt_pk_bf16_f32 v18, v22, v23
	v_cvt_pk_bf16_f32 v19, v24, v25
	v_cvt_pk_bf16_f32 v20, v20, v21
	v_cvt_pk_bf16_f32 v21, v26, v27
	global_store_dwordx4 v[118:119], v[18:21], off
	s_waitcnt vmcnt(7)
	v_lshlrev_b32_e32 v22, 16, v102
	v_and_b32_e32 v23, 0xffff0000, v102
	v_lshlrev_b32_e32 v18, 16, v100
	v_and_b32_e32 v19, 0xffff0000, v100
	v_lshlrev_b32_e32 v20, 16, v101
	v_and_b32_e32 v21, 0xffff0000, v101
	v_lshlrev_b32_e32 v24, 16, v103
	v_and_b32_e32 v25, 0xffff0000, v103
	v_pk_fma_f32 v[16:17], v[16:17], v[72:73], v[20:21]
	v_pk_fma_f32 v[14:15], v[14:15], v[70:71], v[18:19]
	v_pk_fma_f32 v[18:19], v[12:13], v[64:65], v[24:25]
	v_pk_fma_f32 v[12:13], v[10:11], v[62:63], v[22:23]
	v_cvt_pk_bf16_f32 v10, v14, v15
	v_cvt_pk_bf16_f32 v11, v16, v17
	v_cvt_pk_bf16_f32 v12, v12, v13
	v_cvt_pk_bf16_f32 v13, v18, v19
	global_store_dwordx4 v[120:121], v[10:13], off
	s_waitcnt vmcnt(7)
	v_lshlrev_b32_e32 v14, 16, v106
	v_and_b32_e32 v15, 0xffff0000, v106
	v_lshlrev_b32_e32 v10, 16, v104
	v_and_b32_e32 v11, 0xffff0000, v104
	v_lshlrev_b32_e32 v12, 16, v105
	v_and_b32_e32 v13, 0xffff0000, v105
	v_lshlrev_b32_e32 v16, 16, v107
	v_and_b32_e32 v17, 0xffff0000, v107
	v_pk_fma_f32 v[8:9], v[8:9], v[72:73], v[12:13]
	v_pk_fma_f32 v[6:7], v[6:7], v[70:71], v[10:11]
	v_pk_fma_f32 v[10:11], v[4:5], v[64:65], v[16:17]
	v_pk_fma_f32 v[4:5], v[2:3], v[62:63], v[14:15]
	v_cvt_pk_bf16_f32 v2, v6, v7
	v_cvt_pk_bf16_f32 v3, v8, v9
	v_cvt_pk_bf16_f32 v4, v4, v5
	v_cvt_pk_bf16_f32 v5, v10, v11
	global_store_dwordx4 v[74:75], v[2:5], off
	s_andn2_b64 vcc, exec, s[0:1]
	s_mov_b64 s[0:1], -1
	s_cbranch_vccnz .LBB0_2031
	s_andn2_b64 vcc, exec, s[4:5]
	s_cbranch_vccnz .LBB0_2030
	s_barrier
	s_branch .LBB0_2030

; __device__ __forceinline__ float bflo(unsigned u) { return __uint_as_float(u << 16); }
; __device__ __forceinline__ float bfhi(unsigned u) { return __uint_as_float(u & 0xffff0000u); }
; __device__ __forceinline__ void norm_pair_load(NormPair& P, unsigned char* ws, const float* x, const float* ctx, bool first, int l, int which, int sel, int k, int lane) {
;   const float* MODS = (const float*)(ws + WS_MODS); const bf16_t* HB = (const bf16_t*)(ws + WS_HB);
;   const int i = 2 * k;
;   int b, pos; if (sel == 0) { b = i / RB; pos = i - b * RB; } else if (sel == 1) { b = i >> 11; pos = NCTX + (i & 2047); } else { b = i >> 8; pos = i & 255; }
;   const int row = b * RB + pos; P.row = row;
;     ...
;   if (first) { const float* hr = hrow_ptr(ctx, x, row);
; #pragma unroll
;     for (int j = 0; j < 4; ++j) { P.v0[j] = *(const f32x4*)(hr + lane * 4 + 256 * j); P.v1[j] = *(const f32x4*)(hr + DMODEL + lane * 4 + 256 * j); } }
;   else { const bf16_t* hr = HB + (size_t)row * 1024;
; #pragma unroll
;     for (int j = 0; j < 4; ++j) { const u32x2 w = *(const u32x2*)(hr + lane * 4 + 256 * j), w2 = *(const u32x2*)(hr + 1024 + lane * 4 + 256 * j);
;       P.v0[j] = (f32x4){bflo(w.x), bfhi(w.x), bflo(w.y), bfhi(w.y)}; P.v1[j] = (f32x4){bflo(w2.x), bfhi(w2.x), bflo(w2.y), bfhi(w2.y)}; } }
; __device__ __forceinline__ void norm_rows(unsigned char* ws, const float* x, const float* ctx, bool first, int l, int which, int sel, int w0, int wstride, int lane) {
;   const int ppb = (sel == 0 ? RB : sel == 1 ? NLAT : NCTX) >> 1, wpb = wstride >> 4, b = w0 / wpb, wi = w0 - b * wpb, kb = b * ppb, n = (ppb - wi + wpb - 1) / wpb;
;   if (b >= 16 || n <= 0) return;
;   f32x4 sh[4], g[4]; const float* md_cur = nullptr;
;   NormPair A, B; norm_pair_load(A, ws, x, ctx, first, l, which, sel, kb + wi, lane);
.LBB0_2099:
	s_cmp_gt_i32 s94, 16
	s_cselect_b64 s[0:1], -1, 0
	s_cmp_lt_i32 s95, 17
	s_cselect_b64 s[4:5], -1, 0
	s_or_b64 s[0:1], s[0:1], s[4:5]
	s_and_b64 vcc, exec, s[0:1]
	s_cbranch_vccnz .LBB0_2163
	s_waitcnt lgkmcnt(0)
	s_ashr_i32 s8, s33, 1
	s_abs_i32 s4, s8
	v_cvt_f32_u32_e32 v1, s4
	s_lshl_b32 s3, s92, 3
	s_add_i32 s1, s3, s93
	s_ashr_i32 s5, s33, 31
	v_rcp_iflag_f32_e32 v1, v1
	s_ashr_i32 s0, s1, 31
	s_sub_i32 s7, 0, s4
	s_xor_b32 s9, s0, s5
	v_mul_f32_e32 v1, 0x4f7ffffe, v1
	v_cvt_u32_f32_e32 v1, v1
	s_abs_i32 s6, s1
	v_readfirstlane_b32 s0, v1
	s_mul_i32 s7, s7, s0
	s_mul_hi_u32 s7, s0, s7
	s_add_i32 s7, s0, s7
	s_mul_hi_u32 s0, s6, s7
	s_mul_i32 s10, s0, s4
	s_sub_i32 s6, s6, s10
	s_add_i32 s11, s0, 1
	s_sub_i32 s10, s6, s4
	s_cmp_ge_u32 s6, s4
	s_cselect_b32 s0, s11, s0
	s_cselect_b32 s6, s10, s6
	s_add_i32 s10, s0, 1
	s_cmp_ge_u32 s6, s4
	s_cselect_b32 s0, s10, s0
	s_xor_b32 s10, s0, s9
	s_sub_i32 s0, s10, s9
	s_mul_i32 s6, s0, s8
	s_sub_i32 s1, s1, s6
	s_sub_i32 s6, s8, s1
	s_addk_i32 s6, 0x3ff
	s_ashr_i32 s11, s6, 31
	s_abs_i32 s6, s6
	s_mul_hi_u32 s7, s6, s7
	s_xor_b32 s5, s11, s5
	s_mul_i32 s11, s7, s4
	s_sub_i32 s6, s6, s11
	s_add_i32 s11, s7, 1
	s_sub_i32 s12, s6, s4
	s_cmp_ge_u32 s6, s4
	s_cselect_b32 s7, s11, s7
	s_cselect_b32 s6, s12, s6
	s_add_i32 s11, s7, 1
	s_cmp_ge_u32 s6, s4
	s_cselect_b32 s4, s11, s7
	s_xor_b32 s4, s4, s5
	s_sub_i32 s16, s4, s5
	s_cmp_gt_i32 s0, 15
	s_cselect_b64 s[4:5], -1, 0
	s_cmp_lt_i32 s16, 1
	s_cselect_b64 s[6:7], -1, 0
	s_or_b64 s[4:5], s[4:5], s[6:7]
	s_and_b64 vcc, exec, s[4:5]
	s_cbranch_vccnz .LBB0_2113
	s_lshl_b32 s0, s0, 10
	s_add_i32 s4, s1, s0
	s_add_u32 s0, s26, 0x4f00000
	s_addc_u32 s1, s27, 0
	s_lshl_b32 s5, s4, 1
	s_ashr_i32 s4, s4, 10
	s_and_b32 s5, s5, 0x7fe
	s_mul_i32 s6, s4, 0x900
	s_add_i32 s5, s5, s6
	s_add_i32 s4, s4, 17
	s_add_i32 s6, s5, 0x100
	s_mul_hi_i32 s5, s4, 0x6000
	s_mulk_i32 s4, 0x6000
	s_add_u32 s4, s26, s4
	s_addc_u32 s5, s27, s5
	s_add_u32 s4, s4, 0x103000
	s_addc_u32 s5, s5, 0
	s_ashr_i32 s7, s6, 31
	s_lshl_b64 s[12:13], s[6:7], 11
	s_add_u32 s12, s0, s12
	s_addc_u32 s13, s1, s13
	v_lshlrev_b32_e32 v34, 3, v254
	global_load_dwordx2 v[2:3], v34, s[12:13] nt
	global_load_dwordx2 v[4:5], v34, s[12:13] offset:2048 nt
	global_load_dwordx2 v[6:7], v34, s[12:13] offset:512 nt
	global_load_dwordx2 v[8:9], v34, s[12:13] offset:2560 nt
	global_load_dwordx2 v[10:11], v34, s[12:13] offset:1024 nt
	global_load_dwordx2 v[12:13], v34, s[12:13] offset:3072 nt
	global_load_dwordx2 v[14:15], v34, s[12:13] offset:1536 nt
	global_load_dwordx2 v[16:17], v34, s[12:13] offset:3584 nt
	v_mbcnt_lo_u32_b32 v1, -1, 0
	v_mbcnt_hi_u32_b32 v1, -1, v1
	s_waitcnt vmcnt(0)
	v_and_b32_e32 v18, 64, v1
	v_xor_b32_e32 v19, 1, v1
	v_add_u32_e32 v18, 64, v18
	v_mov_b32_e32 v35, 0
	v_xor_b32_e32 v20, 2, v1
	v_cmp_lt_i32_e32 vcc, v19, v18
	s_add_u32 s7, s26, 0x103000
	v_xor_b32_e32 v21, 4, v1
	v_cndmask_b32_e32 v19, v1, v19, vcc
	v_cmp_lt_i32_e32 vcc, v20, v18
	s_addc_u32 s17, s27, 0
	v_lshl_add_u64 v[40:41], s[0:1], 0, v[34:35]
	s_sub_i32 s0, s9, s10
	v_xor_b32_e32 v22, 8, v1
	v_cndmask_b32_e32 v20, v1, v20, vcc
	v_cmp_lt_i32_e32 vcc, v21, v18
	s_add_i32 s1, s0, 2
	v_xor_b32_e32 v23, 16, v1
	v_cndmask_b32_e32 v21, v1, v21, vcc
	v_cmp_lt_i32_e32 vcc, v22, v18
	s_mov_b64 s[12:13], 0x9700000
	s_mul_i32 s1, s8, s1
	s_add_i32 s0, s0, 1
	v_xor_b32_e32 v24, 32, v1
	v_cndmask_b32_e32 v22, v1, v22, vcc
	v_cmp_lt_i32_e32 vcc, v23, v18
	s_add_i32 s11, s93, s1
	s_lshl_b32 s18, s8, 1
	s_lshl_b32 s19, s1, 1
	s_lshl_b32 s1, s10, 11
	s_lshl_b32 s21, s8, 2
	s_mul_i32 s8, s8, s0
	v_cndmask_b32_e32 v23, v1, v23, vcc
	v_cmp_lt_i32_e32 vcc, v24, v18
	s_add_i32 s0, s93, s8
	s_mov_b32 s20, 2
	v_cndmask_b32_e32 v18, v1, v24, vcc
	v_lshlrev_b32_e32 v36, 2, v254
	v_lshlrev_b32_e32 v1, 2, v19
	v_lshlrev_b32_e32 v37, 2, v20
	v_lshlrev_b32_e32 v49, 2, v21
	v_lshlrev_b32_e32 v110, 2, v22
	v_lshlrev_b32_e32 v111, 2, v23
	v_lshlrev_b32_e32 v112, 2, v18
	s_lshl_b32 s22, s8, 1
	v_mov_b32_e32 v76, s6
	s_mov_b32 s6, 0x3a800000
	s_mov_b32 s23, 0x800000
	v_mov_b32_e32 v48, 0x358637bd
	v_lshlrev_b32_e32 v42, 16, v2
	v_and_b32_e32 v43, 0xffff0000, v2
	v_lshlrev_b32_e32 v44, 16, v3
	v_and_b32_e32 v45, 0xffff0000, v3
	v_lshl_add_u64 v[2:3], s[26:27], 0, v[34:35]
	v_lshl_add_u64 v[38:39], v[2:3], 0, s[12:13]
	s_lshl_b32 s12, s10, 10
	s_lshl_b32 s10, s92, 4
	s_add_i32 s1, s1, s10
	s_lshl_b32 s10, s93, 1
	s_add_i32 s11, s11, s12
	s_lshl_b32 s13, s9, 10
	s_add_i32 s1, s1, s10
	s_lshl_b32 s9, s9, 11
	s_add_i32 s0, s0, s12
	v_lshlrev_b32_e32 v46, 16, v4
	v_and_b32_e32 v47, 0xffff0000, v4
	v_lshlrev_b32_e32 v50, 16, v5
	v_and_b32_e32 v51, 0xffff0000, v5
	v_lshlrev_b32_e32 v52, 16, v6
	v_and_b32_e32 v53, 0xffff0000, v6
	v_lshlrev_b32_e32 v54, 16, v7
	v_and_b32_e32 v55, 0xffff0000, v7
	v_lshlrev_b32_e32 v56, 16, v8
	v_and_b32_e32 v57, 0xffff0000, v8
	v_lshlrev_b32_e32 v58, 16, v9
	v_and_b32_e32 v59, 0xffff0000, v9
	v_lshlrev_b32_e32 v60, 16, v10
	v_and_b32_e32 v61, 0xffff0000, v10
	v_lshlrev_b32_e32 v62, 16, v11
	v_and_b32_e32 v63, 0xffff0000, v11
	v_lshlrev_b32_e32 v64, 16, v12
	v_and_b32_e32 v65, 0xffff0000, v12
	v_lshlrev_b32_e32 v66, 16, v13
	v_and_b32_e32 v67, 0xffff0000, v13
	v_lshlrev_b32_e32 v68, 16, v14
	v_and_b32_e32 v69, 0xffff0000, v14
	v_lshlrev_b32_e32 v70, 16, v15
	v_and_b32_e32 v71, 0xffff0000, v15
	v_lshlrev_b32_e32 v72, 16, v16
	v_and_b32_e32 v73, 0xffff0000, v16
	v_lshlrev_b32_e32 v74, 16, v17
	v_and_b32_e32 v75, 0xffff0000, v17
	s_sub_i32 s28, s11, s13
	s_sub_i32 s29, s1, s9
	s_sub_i32 s30, s0, s13
	s_mov_b64 s[0:1], 0
	s_branch .LBB0_2104

; __device__ __forceinline__ void norm_pair_store(const NormPair& P, f32x4 (&sh)[4], f32x4 (&g)[4], const float*& md_cur, unsigned char* ws, int lane) {
;   bf16_t* XN = (bf16_t*)(ws + WS_XN);
;     ...
; #pragma unroll
;     ...
;   float ss0 = 0.f, ss1 = 0.f;
; #pragma unroll
;   for (int j = 0; j < 4; ++j) { ss0 += (P.v0[j][0] * P.v0[j][0] + P.v0[j][1] * P.v0[j][1]) + (P.v0[j][2] * P.v0[j][2] + P.v0[j][3] * P.v0[j][3]); ss1 += (P.v1[j][0] * P.v1[j][0] + P.v1[j][1] * P.v1[j][1]) + (P.v1[j][2] * P.v1[j][2] + P.v1[j][3] * P.v1[j][3]); }
;   const float rs0 = rsqrtf(wave_sum64(ss0) * (1.f / 1024.f) + EPS_N), rs1 = rsqrtf(wave_sum64(ss1) * (1.f / 1024.f) + EPS_N);
; __device__ __forceinline__ void norm_rows(unsigned char* ws, const float* x, const float* ctx, bool first, int l, int which, int sel, int w0, int wstride, int lane) {
;     ...
;   for (int j = 0; j < n; j += 2) {
;     if (j + 1 < n) norm_pair_load(B, ws, x, ctx, first, l, which, sel, kb + wi + wpb * (j + 1), lane);
;     norm_pair_store(A, sh, g, md_cur, ws, lane);
.LBB0_2104:
	s_add_i32 s9, s20, -1
	s_cmp_lt_i32 s9, s16
	s_cselect_b64 s[14:15], -1, 0
	s_cmp_ge_i32 s9, s16
	s_cbranch_scc1 .LBB0_2106
	s_add_i32 s8, s3, s30
	s_add_i32 s9, s22, s29
	s_ashr_i32 s10, s8, 10
	s_and_b32 s8, s9, 0x7fe
	s_mul_i32 s9, s10, 0x900
	s_add_i32 s8, s8, s9
	s_add_i32 s9, s10, 17
	s_addk_i32 s8, 0x100
	s_mul_hi_i32 s11, s9, 0x6000
	s_mulk_i32 s9, 0x6000
	s_add_u32 s10, s7, s9
	s_addc_u32 s11, s17, s11
	s_ashr_i32 s9, s8, 31
	s_lshl_b64 s[12:13], s[8:9], 11
	v_lshl_add_u64 v[78:79], v[40:41], 0, s[12:13]
	global_load_dwordx2 v[80:81], v[78:79], off nt
	global_load_dwordx2 v[84:85], v[78:79], off offset:2048 nt
	global_load_dwordx2 v[88:89], v[78:79], off offset:512 nt
	global_load_dwordx2 v[90:91], v[78:79], off offset:2560 nt
	global_load_dwordx2 v[96:97], v[78:79], off offset:1024 nt
	global_load_dwordx2 v[102:103], v[78:79], off offset:3072 nt
	global_load_dwordx2 v[104:105], v[78:79], off offset:1536 nt
	global_load_dwordx2 v[108:109], v[78:79], off offset:3584 nt
	s_waitcnt vmcnt(7)
	v_lshlrev_b32_e32 v78, 16, v80
	v_and_b32_e32 v79, 0xffff0000, v80
	v_lshlrev_b32_e32 v86, 16, v81
	v_and_b32_e32 v87, 0xffff0000, v81
	s_waitcnt vmcnt(6)
	v_lshlrev_b32_e32 v82, 16, v84
	v_and_b32_e32 v83, 0xffff0000, v84
	v_lshlrev_b32_e32 v92, 16, v85
	v_and_b32_e32 v93, 0xffff0000, v85
	s_waitcnt vmcnt(5)
	v_lshlrev_b32_e32 v80, 16, v88
	v_and_b32_e32 v81, 0xffff0000, v88
	v_lshlrev_b32_e32 v94, 16, v89
	v_and_b32_e32 v95, 0xffff0000, v89
	s_waitcnt vmcnt(4)
	v_lshlrev_b32_e32 v88, 16, v90
	v_and_b32_e32 v89, 0xffff0000, v90
	v_lshlrev_b32_e32 v98, 16, v91
	v_and_b32_e32 v99, 0xffff0000, v91
	s_waitcnt vmcnt(3)
	v_lshlrev_b32_e32 v84, 16, v96
	v_and_b32_e32 v85, 0xffff0000, v96
	v_lshlrev_b32_e32 v100, 16, v97
	v_and_b32_e32 v101, 0xffff0000, v97
	s_waitcnt vmcnt(2)
	v_lshlrev_b32_e32 v96, 16, v102
	v_and_b32_e32 v97, 0xffff0000, v102
	v_lshlrev_b32_e32 v102, 16, v103
	v_and_b32_e32 v103, 0xffff0000, v103
	s_waitcnt vmcnt(1)
	v_lshlrev_b32_e32 v90, 16, v104
	v_and_b32_e32 v91, 0xffff0000, v104
	v_lshlrev_b32_e32 v104, 16, v105
	v_and_b32_e32 v105, 0xffff0000, v105
	s_waitcnt vmcnt(0)
	v_lshlrev_b32_e32 v106, 16, v108
	v_and_b32_e32 v107, 0xffff0000, v108
	v_lshlrev_b32_e32 v108, 16, v109
	v_and_b32_e32 v109, 0xffff0000, v109
.LBB0_2106:
	s_cmp_eq_u64 s[4:5], s[0:1]
	s_cbranch_scc1 .LBB0_2108
	v_lshlrev_b32_e32 v34, 2, v36
	v_lshl_add_u64 v[2:3], s[4:5], 0, v[34:35]
	v_add_co_u32_e32 v114, vcc, 0x1000, v2
	s_nop 1
	v_addc_co_u32_e32 v115, vcc, 0, v3, vcc
	global_load_dwordx4 v[18:21], v[114:115], off nt
	global_load_dwordx4 v[22:25], v[114:115], off offset:1024 nt
	global_load_dwordx4 v[26:29], v[114:115], off offset:2048 nt
	global_load_dwordx4 v[2:5], v34, s[4:5] nt
	global_load_dwordx4 v[6:9], v34, s[4:5] offset:1024 nt
	global_load_dwordx4 v[30:33], v[114:115], off offset:3072 nt
	global_load_dwordx4 v[14:17], v34, s[4:5] offset:2048 nt
	global_load_dwordx4 v[10:13], v34, s[4:5] offset:3072 nt
	s_waitcnt vmcnt(7)
	v_pk_add_f32 v[20:21], v[20:21], 1.0 op_sel_hi:[1,0]
	v_pk_add_f32 v[18:19], v[18:19], 1.0 op_sel_hi:[1,0]
	s_waitcnt vmcnt(6)
	v_pk_add_f32 v[24:25], v[24:25], 1.0 op_sel_hi:[1,0]
	v_pk_add_f32 v[22:23], v[22:23], 1.0 op_sel_hi:[1,0]
	s_waitcnt vmcnt(5)
	v_pk_add_f32 v[28:29], v[28:29], 1.0 op_sel_hi:[1,0]
	v_pk_add_f32 v[26:27], v[26:27], 1.0 op_sel_hi:[1,0]
	s_waitcnt vmcnt(2)
	v_pk_add_f32 v[32:33], v[32:33], 1.0 op_sel_hi:[1,0]
	v_pk_add_f32 v[30:31], v[30:31], 1.0 op_sel_hi:[1,0]
.LBB0_2108:
	v_pk_mul_f32 v[114:115], v[44:45], v[44:45]
	v_pk_mul_f32 v[116:117], v[42:43], v[42:43]
	v_mul_f32_e32 v34, v60, v60
	v_pk_mov_b32 v[118:119], v[116:117], v[114:115] op_sel:[1,0]
	v_mov_b32_e32 v117, v115
	v_pk_add_f32 v[114:115], v[118:119], v[116:117]
	v_pk_mul_f32 v[116:117], v[50:51], v[50:51]
	v_pk_mul_f32 v[118:119], v[46:47], v[46:47]
	v_pk_add_f32 v[114:115], v[114:115], v[114:115] op_sel_hi:[0,1]
	v_pk_mov_b32 v[120:121], v[118:119], v[116:117] op_sel:[1,0]
	v_mov_b32_e32 v119, v117
	v_pk_add_f32 v[116:117], v[120:121], v[118:119]
	v_pk_mul_f32 v[118:119], v[54:55], v[54:55]
	v_pk_mul_f32 v[120:121], v[52:53], v[52:53]
	v_pk_add_f32 v[116:117], v[116:117], v[116:117] op_sel_hi:[0,1]
	v_pk_mov_b32 v[122:123], v[120:121], v[118:119] op_sel:[1,0]
	v_mov_b32_e32 v121, v119
	v_pk_add_f32 v[118:119], v[122:123], v[120:121]
	v_pk_mul_f32 v[120:121], v[58:59], v[58:59]
	v_pk_mul_f32 v[122:123], v[56:57], v[56:57]
	v_pk_add_f32 v[118:119], v[118:119], v[118:119] op_sel_hi:[0,1]
	v_pk_mov_b32 v[124:125], v[122:123], v[120:121] op_sel:[1,0]
	v_mov_b32_e32 v123, v121
	v_pk_add_f32 v[120:121], v[124:125], v[122:123]
	v_pk_fma_f32 v[122:123], v[60:61], v[60:61], v[34:35] op_sel_hi:[1,1,0]
	v_mul_f32_e32 v34, v62, v62
	v_pk_fma_f32 v[124:125], v[62:63], v[62:63], v[34:35] op_sel_hi:[1,1,0]
	v_mul_f32_e32 v34, v64, v64
	v_pk_fma_f32 v[126:127], v[64:65], v[64:65], v[34:35] op_sel_hi:[1,1,0]
	v_mul_f32_e32 v34, v66, v66
	v_pk_add_f32 v[120:121], v[120:121], v[120:121] op_sel_hi:[0,1]
	v_pk_fma_f32 v[128:129], v[66:67], v[66:67], v[34:35] op_sel_hi:[1,1,0]
	v_mul_f32_e32 v122, v68, v68
	v_mul_f32_e32 v124, v69, v69
	v_mul_f32_e32 v114, v70, v70
	v_mul_f32_e32 v118, v71, v71
	v_mul_f32_e32 v126, v72, v72
	v_mul_f32_e32 v128, v73, v73
	v_mul_f32_e32 v116, v74, v74
	v_mul_f32_e32 v120, v75, v75
	v_pk_add_f32 v[122:123], v[122:123], v[124:125]
	v_pk_add_f32 v[114:115], v[114:115], v[118:119]
	v_pk_add_f32 v[118:119], v[126:127], v[128:129]
	v_pk_add_f32 v[116:117], v[116:117], v[120:121]
	v_pk_add_f32 v[114:115], v[122:123], v[114:115]
	v_pk_add_f32 v[116:117], v[118:119], v[116:117]
	v_mov_b32_e32 v119, v114
	v_mov_b32_e32 v118, v116
	v_mov_b32_e32 v114, v117
	v_pk_add_f32 v[114:115], v[118:119], v[114:115]
	ds_bpermute_b32 v117, v1, v115
	ds_bpermute_b32 v116, v1, v114
	s_mov_b64 s[12:13], -1
	v_readfirstlane_b32 s9, v0
	v_readfirstlane_b32 s31, v0
	v_readfirstlane_b32 s34, v0
	s_waitcnt lgkmcnt(0)
; __device__ __forceinline__ unsigned pk2(float lo, float hi) { f32x2 v = {lo, hi}; bf16x2_t b = __builtin_convertvector(v, bf16x2_t); return __builtin_bit_cast(unsigned, b); }
; __device__ __forceinline__ void norm_pair_store(const NormPair& P, f32x4 (&sh)[4], f32x4 (&g)[4], const float*& md_cur, unsigned char* ws, int lane) {
;     ...
;   const float rs0 = rsqrtf(wave_sum64(ss0) * (1.f / 1024.f) + EPS_N), rs1 = rsqrtf(wave_sum64(ss1) * (1.f / 1024.f) + EPS_N);
; #pragma unroll
;   for (int j = 0; j < 4; ++j) {
;     const f32x4 o0 = P.v0[j] * rs0 * g[j] + sh[j], o1 = P.v1[j] * rs1 * g[j] + sh[j]; u32x2 w, w2; w.x = pk2(o0[0], o0[1]); w.y = pk2(o0[2], o0[3]); w2.x = pk2(o1[0], o1[1]); w2.y = pk2(o1[2], o1[3]);
;     *(u32x2*)(XN + (size_t)P.row * 1024 + lane * 4 + 256 * j) = w; *(u32x2*)(XN + (size_t)(P.row + 1) * 1024 + lane * 4 + 256 * j) = w2; }
; }
; __device__ __forceinline__ void norm_rows(unsigned char* ws, const float* x, const float* ctx, bool first, int l, int which, int sel, int w0, int wstride, int lane) {
;   const int ppb = (sel == 0 ? RB : sel == 1 ? NLAT : NCTX) >> 1, wpb = wstride >> 4, b = w0 / wpb, wi = w0 - b * wpb, kb = b * ppb, n = (ppb - wi + wpb - 1) / wpb;
;   if (b >= 16 || n <= 0) return;
;   f32x4 sh[4], g[4]; const float* md_cur = nullptr;
;   NormPair A, B; norm_pair_load(A, ws, x, ctx, first, l, which, sel, kb + wi, lane);
;   for (int j = 0; j < n; j += 2) {
;     if (j + 1 < n) norm_pair_load(B, ws, x, ctx, first, l, which, sel, kb + wi + wpb * (j + 1), lane);
;     norm_pair_store(A, sh, g, md_cur, ws, lane);
;     if (j + 1 >= n) break;
;     if (j + 2 < n) norm_pair_load(A, ws, x, ctx, first, l, which, sel, kb + wi + wpb * (j + 2), lane);
	v_pk_add_f32 v[114:115], v[114:115], v[116:117]
	ds_bpermute_b32 v117, v37, v115
	ds_bpermute_b32 v116, v37, v114
	v_readfirstlane_b32 s35, v0
	s_waitcnt lgkmcnt(0)
	v_pk_add_f32 v[114:115], v[114:115], v[116:117]
	ds_bpermute_b32 v117, v49, v115
	ds_bpermute_b32 v116, v49, v114
	s_waitcnt lgkmcnt(0)
	v_pk_add_f32 v[114:115], v[114:115], v[116:117]
	ds_bpermute_b32 v117, v110, v115
	ds_bpermute_b32 v116, v110, v114
	s_waitcnt lgkmcnt(0)
	v_pk_add_f32 v[114:115], v[114:115], v[116:117]
	ds_bpermute_b32 v117, v111, v115
	ds_bpermute_b32 v116, v111, v114
	s_waitcnt lgkmcnt(0)
	v_pk_add_f32 v[114:115], v[114:115], v[116:117]
	ds_bpermute_b32 v117, v112, v115
	ds_bpermute_b32 v116, v112, v114
	s_waitcnt lgkmcnt(0)
	v_pk_add_f32 v[114:115], v[114:115], v[116:117]
	s_nop 0
	v_pk_fma_f32 v[114:115], v[114:115], s[6:7], v[48:49] op_sel_hi:[1,0,0]
	s_nop 0
	v_mul_f32_e32 v34, 0x4b800000, v115
	v_cmp_gt_f32_e32 vcc, s23, v115
	v_mul_f32_e32 v77, 0x4b800000, v114
	v_cmp_gt_f32_e64 s[0:1], s23, v114
	v_cndmask_b32_e32 v34, v115, v34, vcc
	v_rsq_f32_e32 v34, v34
	v_cndmask_b32_e64 v77, v114, v77, s[0:1]
	v_rsq_f32_e32 v77, v77
	v_mul_f32_e32 v113, 0x45800000, v34
	v_cndmask_b32_e32 v34, v34, v113, vcc
	v_mul_f32_e32 v113, 0x45800000, v77
	v_cndmask_b32_e64 v114, v77, v113, s[0:1]
	v_pk_mul_f32 v[116:117], v[34:35], v[42:43] op_sel_hi:[0,1]
	v_pk_mul_f32 v[118:119], v[34:35], v[44:45] op_sel_hi:[0,1]
	v_pk_mul_f32 v[120:121], v[114:115], v[46:47] op_sel_hi:[0,1]
	v_pk_fma_f32 v[118:119], v[20:21], v[118:119], v[4:5]
	v_pk_fma_f32 v[116:117], v[18:19], v[116:117], v[2:3]
	v_pk_mul_f32 v[122:123], v[114:115], v[50:51] op_sel_hi:[0,1]
	v_pk_fma_f32 v[120:121], v[18:19], v[120:121], v[2:3]
	v_ashrrev_i32_e32 v77, 31, v76
	v_pk_fma_f32 v[122:123], v[20:21], v[122:123], v[4:5]
	v_cvt_pk_bf16_f32 v116, v116, v117
	v_cvt_pk_bf16_f32 v117, v118, v119
	v_cvt_pk_bf16_f32 v118, v120, v121
	v_lshlrev_b64 v[120:121], 11, v[76:77]
	v_cvt_pk_bf16_f32 v119, v122, v123
	v_lshl_add_u64 v[120:121], v[38:39], 0, v[120:121]
	global_store_dwordx2 v[120:121], v[116:117], off
	global_store_dwordx2 v[120:121], v[118:119], off offset:2048
	v_pk_mul_f32 v[116:117], v[34:35], v[52:53] op_sel_hi:[0,1]
	v_pk_mul_f32 v[118:119], v[34:35], v[54:55] op_sel_hi:[0,1]
	v_pk_mul_f32 v[122:123], v[114:115], v[56:57] op_sel_hi:[0,1]
	v_pk_mul_f32 v[124:125], v[114:115], v[58:59] op_sel_hi:[0,1]
	v_pk_fma_f32 v[118:119], v[24:25], v[118:119], v[8:9]
	v_pk_fma_f32 v[116:117], v[22:23], v[116:117], v[6:7]
	v_pk_fma_f32 v[124:125], v[24:25], v[124:125], v[8:9]
	v_pk_fma_f32 v[122:123], v[22:23], v[122:123], v[6:7]
	v_cvt_pk_bf16_f32 v116, v116, v117
	v_cvt_pk_bf16_f32 v117, v118, v119
	v_cvt_pk_bf16_f32 v118, v122, v123
	v_cvt_pk_bf16_f32 v119, v124, v125
	global_store_dwordx2 v[120:121], v[116:117], off offset:512
	global_store_dwordx2 v[120:121], v[118:119], off offset:2560
	v_pk_mul_f32 v[116:117], v[34:35], v[60:61] op_sel_hi:[0,1]
	v_pk_mul_f32 v[118:119], v[34:35], v[62:63] op_sel_hi:[0,1]
	v_pk_mul_f32 v[122:123], v[114:115], v[64:65] op_sel_hi:[0,1]
	v_pk_mul_f32 v[124:125], v[114:115], v[66:67] op_sel_hi:[0,1]
	s_waitcnt vmcnt(5)
	v_pk_fma_f32 v[118:119], v[28:29], v[118:119], v[16:17]
	v_pk_fma_f32 v[116:117], v[26:27], v[116:117], v[14:15]
	v_pk_fma_f32 v[124:125], v[28:29], v[124:125], v[16:17]
	v_pk_fma_f32 v[122:123], v[26:27], v[122:123], v[14:15]
	v_cvt_pk_bf16_f32 v116, v116, v117
	v_cvt_pk_bf16_f32 v117, v118, v119
	v_cvt_pk_bf16_f32 v118, v122, v123
	v_cvt_pk_bf16_f32 v119, v124, v125
	global_store_dwordx2 v[120:121], v[116:117], off offset:1024
	global_store_dwordx2 v[120:121], v[118:119], off offset:3072
	v_pk_mul_f32 v[116:117], v[34:35], v[68:69] op_sel_hi:[0,1]
	v_pk_mul_f32 v[118:119], v[34:35], v[70:71] op_sel_hi:[0,1]
	s_waitcnt vmcnt(6)
	v_pk_fma_f32 v[118:119], v[32:33], v[118:119], v[12:13]
	v_pk_fma_f32 v[116:117], v[30:31], v[116:117], v[10:11]
	v_pk_mul_f32 v[122:123], v[114:115], v[72:73] op_sel_hi:[0,1]
	v_pk_mul_f32 v[114:115], v[114:115], v[74:75] op_sel_hi:[0,1]
	v_pk_fma_f32 v[114:115], v[32:33], v[114:115], v[12:13]
	v_pk_fma_f32 v[122:123], v[30:31], v[122:123], v[10:11]
	v_cvt_pk_bf16_f32 v116, v116, v117
	v_cvt_pk_bf16_f32 v117, v118, v119
	s_andn2_b64 vcc, exec, s[14:15]
	v_cvt_pk_bf16_f32 v118, v122, v123
	v_cvt_pk_bf16_f32 v119, v114, v115
	global_store_dwordx2 v[120:121], v[116:117], off offset:1536
	global_store_dwordx2 v[120:121], v[118:119], off offset:3584
	s_cbranch_vccnz .LBB0_2103
	s_cmp_ge_i32 s20, s16
	s_cselect_b64 s[12:13], -1, 0
	s_and_b64 vcc, exec, s[12:13]
	s_mov_b64 s[14:15], s[4:5]
	s_cbranch_vccnz .LBB0_2111
	s_add_i32 s0, s3, s28
	s_add_i32 s1, s19, s29
	s_ashr_i32 s9, s0, 10
	s_and_b32 s0, s1, 0x7fe
	s_mul_i32 s1, s9, 0x900
	s_add_i32 s0, s0, s1
	s_add_i32 s1, s9, 17
	s_addk_i32 s0, 0x100
	s_mul_hi_i32 s9, s1, 0x6000
	s_mulk_i32 s1, 0x6000
	s_add_u32 s14, s7, s1
	s_addc_u32 s15, s17, s9
	s_ashr_i32 s1, s0, 31
	s_lshl_b64 s[34:35], s[0:1], 11
	v_lshl_add_u64 v[42:43], v[40:41], 0, s[34:35]
	global_load_dwordx2 v[44:45], v[42:43], off nt
	global_load_dwordx2 v[50:51], v[42:43], off offset:2048 nt
	global_load_dwordx2 v[54:55], v[42:43], off offset:512 nt
	global_load_dwordx2 v[58:59], v[42:43], off offset:2560 nt
	global_load_dwordx2 v[62:63], v[42:43], off offset:1024 nt
	global_load_dwordx2 v[66:67], v[42:43], off offset:3072 nt
	global_load_dwordx2 v[70:71], v[42:43], off offset:1536 nt
	global_load_dwordx2 v[74:75], v[42:43], off offset:3584 nt
	v_mov_b32_e32 v76, s0
	s_waitcnt vmcnt(7)
	v_lshlrev_b32_e32 v42, 16, v44
	v_and_b32_e32 v43, 0xffff0000, v44
	v_lshlrev_b32_e32 v44, 16, v45
	v_and_b32_e32 v45, 0xffff0000, v45
	s_waitcnt vmcnt(6)
	v_lshlrev_b32_e32 v46, 16, v50
	v_and_b32_e32 v47, 0xffff0000, v50
	v_lshlrev_b32_e32 v50, 16, v51
	v_and_b32_e32 v51, 0xffff0000, v51
	s_waitcnt vmcnt(5)
	v_lshlrev_b32_e32 v52, 16, v54
	v_and_b32_e32 v53, 0xffff0000, v54
	v_lshlrev_b32_e32 v54, 16, v55
	v_and_b32_e32 v55, 0xffff0000, v55
	s_waitcnt vmcnt(4)
	v_lshlrev_b32_e32 v56, 16, v58
	v_and_b32_e32 v57, 0xffff0000, v58
	v_lshlrev_b32_e32 v58, 16, v59
	v_and_b32_e32 v59, 0xffff0000, v59
	s_waitcnt vmcnt(3)
	v_lshlrev_b32_e32 v60, 16, v62
	v_and_b32_e32 v61, 0xffff0000, v62
	v_lshlrev_b32_e32 v62, 16, v63
	v_and_b32_e32 v63, 0xffff0000, v63
	s_waitcnt vmcnt(2)
	v_lshlrev_b32_e32 v64, 16, v66
	v_and_b32_e32 v65, 0xffff0000, v66
	v_lshlrev_b32_e32 v66, 16, v67
	v_and_b32_e32 v67, 0xffff0000, v67
	s_waitcnt vmcnt(1)
	v_lshlrev_b32_e32 v68, 16, v70
	v_and_b32_e32 v69, 0xffff0000, v70
	v_lshlrev_b32_e32 v70, 16, v71
	v_and_b32_e32 v71, 0xffff0000, v71
	s_waitcnt vmcnt(0)
	v_lshlrev_b32_e32 v72, 16, v74
	v_and_b32_e32 v73, 0xffff0000, v74
	v_lshlrev_b32_e32 v74, 16, v75
	v_and_b32_e32 v75, 0xffff0000, v75
; __device__ __forceinline__ void norm_pair_store(const NormPair& P, f32x4 (&sh)[4], f32x4 (&g)[4], const float*& md_cur, unsigned char* ws, int lane) {
;     ...
; #pragma unroll
.LBB0_2111:
	s_cmp_eq_u64 s[10:11], s[4:5]
	s_cbranch_scc1 .LBB0_2102
	v_lshlrev_b32_e32 v34, 2, v36
	v_lshl_add_u64 v[2:3], s[10:11], 0, v[34:35]
	v_add_co_u32_e32 v114, vcc, 0x1000, v2
	s_mov_b64 s[4:5], s[10:11]
	s_nop 0
	v_addc_co_u32_e32 v115, vcc, 0, v3, vcc
	global_load_dwordx4 v[18:21], v[114:115], off nt
	global_load_dwordx4 v[22:25], v[114:115], off offset:1024 nt
	global_load_dwordx4 v[26:29], v[114:115], off offset:2048 nt
	global_load_dwordx4 v[30:33], v[114:115], off offset:3072 nt
	global_load_dwordx4 v[2:5], v34, s[10:11] nt
	global_load_dwordx4 v[6:9], v34, s[10:11] offset:1024 nt
	global_load_dwordx4 v[14:17], v34, s[10:11] offset:2048 nt
	global_load_dwordx4 v[10:13], v34, s[10:11] offset:3072 nt
	s_waitcnt vmcnt(7)
	v_pk_add_f32 v[20:21], v[20:21], 1.0 op_sel_hi:[1,0]
	v_pk_add_f32 v[18:19], v[18:19], 1.0 op_sel_hi:[1,0]
	s_waitcnt vmcnt(6)
	v_pk_add_f32 v[24:25], v[24:25], 1.0 op_sel_hi:[1,0]
	v_pk_add_f32 v[22:23], v[22:23], 1.0 op_sel_hi:[1,0]
	s_waitcnt vmcnt(5)
	v_pk_add_f32 v[28:29], v[28:29], 1.0 op_sel_hi:[1,0]
	v_pk_add_f32 v[26:27], v[26:27], 1.0 op_sel_hi:[1,0]
	s_waitcnt vmcnt(4)
	v_pk_add_f32 v[32:33], v[32:33], 1.0 op_sel_hi:[1,0]
	v_pk_add_f32 v[30:31], v[30:31], 1.0 op_sel_hi:[1,0]
	s_branch .LBB0_2102

; __device__ __forceinline__ float bflo(unsigned u) { return __uint_as_float(u << 16); }
; __device__ __forceinline__ float bfhi(unsigned u) { return __uint_as_float(u & 0xffff0000u); }
; __device__ __forceinline__ void store8(bf16_t* p, const f32x4& a, const f32x4& b) { u32x4 w; w.x = pk2(a[0], a[1]); w.y = pk2(a[2], a[3]); w.z = pk2(b[0], b[1]); w.w = pk2(b[2], b[3]); *(u32x4*)p = w; }
;     __device__ __forceinline__ void operator()(const f32x4 (&acc)[2][2][4][2], const pg8::Unit& u, int wr, int wc, int fr, int fq, int buf) const {
;     ...
;             for (int bj = 0; bj < 2; ++bj) {
;                 const int c0 = u.pn * 256 + bj * 128 + wc * 32 + 8 * fq; const f32x4 g0 = *(const f32x4*)(gt + c0), g1 = *(const f32x4*)(gt + c0 + 4);
;                 if (first) { f32x4 h0[8], h1[8];
; #pragma unroll
;                     for (int q = 0; q < 8; ++q) { const size_t off = (size_t)((q >> 2) * 128 + (q & 3) * 16 + rloc0) * DMODEL + c0; h0[q] = *(const f32x4*)(hi_ + off); h1[q] = *(const f32x4*)(hi_ + off + 4); }
;                     __builtin_amdgcn_sched_barrier(0);
; #pragma unroll
;                     for (int q = 0; q < 8; ++q) { const size_t off = (size_t)((q >> 2) * 128 + (q & 3) * 16 + rloc0) * DMODEL + c0;
;                         store8(HB + off, h0[q] + g0 * acc[q >> 2][bj][q & 3][0], h1[q] + g1 * acc[q >> 2][bj][q & 3][1]); }
;                 } else { u32x4 hw[8];
; #pragma unroll
;                     for (int q = 0; q < 8; ++q) { const size_t off = (size_t)((q >> 2) * 128 + (q & 3) * 16 + rloc0) * DMODEL + c0; hw[q] = *(const u32x4*)(HB + off); }
;                     __builtin_amdgcn_sched_barrier(0);
; #pragma unroll
;                     for (int q = 0; q < 8; ++q) { const size_t off = (size_t)((q >> 2) * 128 + (q & 3) * 16 + rloc0) * DMODEL + c0;
;                         const f32x4 h0 = (f32x4){bflo(hw[q].x), bfhi(hw[q].x), bflo(hw[q].y), bfhi(hw[q].y)}, h1 = (f32x4){bflo(hw[q].z), bfhi(hw[q].z), bflo(hw[q].w), bfhi(hw[q].w)};
;                         store8(HB + off, h0 + g0 * acc[q >> 2][bj][q & 3][0], h1 + g1 * acc[q >> 2][bj][q & 3][1]); }
.LBB0_2344:
	s_ashr_i32 s19, s18, 31
	s_lshl_b64 s[4:5], s[18:19], 19
	s_add_u32 s4, s50, s4
	s_addc_u32 s5, s51, s5
	s_lshl_b64 s[18:19], s[20:21], 2
	s_add_u32 s18, s43, s18
	s_addc_u32 s19, s44, s19
	s_lshl_b32 s13, s56, 8
	v_add_u32_e32 v172, s45, v131
	s_or_b32 s13, s13, s46
	v_lshl_add_u32 v156, v130, 3, s13
	v_ashrrev_i32_e32 v173, 31, v172
	v_add_u32_e32 v162, 32, v172
	v_add_u32_e32 v166, 0x80, v172
	v_add_u32_e32 v170, 0xa0, v172
	v_ashrrev_i32_e32 v157, 31, v156
	v_lshlrev_b64 v[158:159], 11, v[172:173]
	v_add_u32_e32 v160, 16, v172
	v_ashrrev_i32_e32 v163, 31, v162
	v_add_u32_e32 v164, 48, v172
	v_ashrrev_i32_e32 v167, 31, v166
	v_add_u32_e32 v168, 0x90, v172
	v_ashrrev_i32_e32 v171, 31, v170
	v_add_u32_e32 v172, 0xb0, v172
	v_lshl_add_u64 v[174:175], v[156:157], 1, s[4:5]
	v_ashrrev_i32_e32 v161, 31, v160
	v_lshlrev_b64 v[162:163], 11, v[162:163]
	v_ashrrev_i32_e32 v165, 31, v164
	v_lshlrev_b64 v[166:167], 11, v[166:167]
	v_ashrrev_i32_e32 v169, 31, v168
	v_lshlrev_b64 v[170:171], 11, v[170:171]
	v_ashrrev_i32_e32 v173, 31, v172
	v_lshl_add_u64 v[154:155], v[156:157], 2, s[18:19]
	v_lshl_add_u64 v[214:215], v[174:175], 0, v[158:159]
	v_lshlrev_b64 v[160:161], 11, v[160:161]
	v_lshl_add_u64 v[218:219], v[174:175], 0, v[162:163]
	v_lshlrev_b64 v[164:165], 11, v[164:165]
	v_lshl_add_u64 v[222:223], v[174:175], 0, v[166:167]
	v_lshlrev_b64 v[168:169], 11, v[168:169]
	v_lshl_add_u64 v[226:227], v[174:175], 0, v[170:171]
	v_lshlrev_b64 v[172:173], 11, v[172:173]
	global_load_dwordx4 v[130:133], v[154:155], off offset:16 nt
	global_load_dwordx4 v[134:137], v[154:155], off nt
	v_lshl_add_u64 v[216:217], v[174:175], 0, v[160:161]
	global_load_dwordx4 v[182:185], v[214:215], off nt
	global_load_dwordx4 v[186:189], v[216:217], off nt
	v_lshl_add_u64 v[220:221], v[174:175], 0, v[164:165]
	global_load_dwordx4 v[190:193], v[218:219], off nt
	global_load_dwordx4 v[194:197], v[220:221], off nt
	v_lshl_add_u64 v[224:225], v[174:175], 0, v[168:169]
	global_load_dwordx4 v[198:201], v[222:223], off nt
	global_load_dwordx4 v[202:205], v[224:225], off nt
	v_lshl_add_u64 v[174:175], v[174:175], 0, v[172:173]
	global_load_dwordx4 v[206:209], v[226:227], off nt
	global_load_dwordx4 v[210:213], v[174:175], off nt
	s_waitcnt vmcnt(0)
	v_lshlrev_b32_e32 v228, 16, v182
	v_and_b32_e32 v229, 0xffff0000, v182
	v_lshlrev_b32_e32 v182, 16, v183
	v_and_b32_e32 v183, 0xffff0000, v183
	v_lshlrev_b32_e32 v230, 16, v184
	v_and_b32_e32 v231, 0xffff0000, v184
	v_lshlrev_b32_e32 v184, 16, v185
	v_and_b32_e32 v185, 0xffff0000, v185
	v_pk_fma_f32 v[128:129], v[128:129], v[136:137], v[182:183]
	v_pk_fma_f32 v[126:127], v[126:127], v[134:135], v[228:229]
	v_pk_fma_f32 v[182:183], v[124:125], v[132:133], v[184:185]
	v_pk_fma_f32 v[124:125], v[122:123], v[130:131], v[230:231]
	v_cvt_pk_bf16_f32 v122, v126, v127
	v_cvt_pk_bf16_f32 v123, v128, v129
	v_cvt_pk_bf16_f32 v124, v124, v125
	v_cvt_pk_bf16_f32 v125, v182, v183
	global_store_dwordx4 v[214:215], v[122:125], off
	v_lshlrev_b32_e32 v126, 16, v188
	v_and_b32_e32 v127, 0xffff0000, v188
	v_lshlrev_b32_e32 v122, 16, v186
	v_and_b32_e32 v123, 0xffff0000, v186
	v_lshlrev_b32_e32 v124, 16, v187
	v_and_b32_e32 v125, 0xffff0000, v187
	v_lshlrev_b32_e32 v128, 16, v189
	v_and_b32_e32 v129, 0xffff0000, v189
	v_pk_fma_f32 v[120:121], v[120:121], v[136:137], v[124:125]
	v_pk_fma_f32 v[118:119], v[118:119], v[134:135], v[122:123]
	v_pk_fma_f32 v[122:123], v[116:117], v[132:133], v[128:129]
	v_pk_fma_f32 v[116:117], v[114:115], v[130:131], v[126:127]
	v_cvt_pk_bf16_f32 v114, v118, v119
	v_cvt_pk_bf16_f32 v115, v120, v121
	v_cvt_pk_bf16_f32 v116, v116, v117
	v_cvt_pk_bf16_f32 v117, v122, v123
	global_store_dwordx4 v[216:217], v[114:117], off
	v_lshlrev_b32_e32 v118, 16, v192
	v_and_b32_e32 v119, 0xffff0000, v192
	v_lshlrev_b32_e32 v114, 16, v190
	v_and_b32_e32 v115, 0xffff0000, v190
	v_lshlrev_b32_e32 v116, 16, v191
	v_and_b32_e32 v117, 0xffff0000, v191
	v_lshlrev_b32_e32 v120, 16, v193
	v_and_b32_e32 v121, 0xffff0000, v193
	v_pk_fma_f32 v[112:113], v[112:113], v[136:137], v[116:117]
	v_pk_fma_f32 v[110:111], v[110:111], v[134:135], v[114:115]
	v_pk_fma_f32 v[114:115], v[108:109], v[132:133], v[120:121]
	v_pk_fma_f32 v[108:109], v[106:107], v[130:131], v[118:119]
	v_cvt_pk_bf16_f32 v106, v110, v111
	v_cvt_pk_bf16_f32 v107, v112, v113
	v_cvt_pk_bf16_f32 v108, v108, v109
	v_cvt_pk_bf16_f32 v109, v114, v115
	global_store_dwordx4 v[218:219], v[106:109], off
	v_lshlrev_b32_e32 v110, 16, v196
	v_and_b32_e32 v111, 0xffff0000, v196
	v_lshlrev_b32_e32 v106, 16, v194
	v_and_b32_e32 v107, 0xffff0000, v194
	v_lshlrev_b32_e32 v108, 16, v195
	v_and_b32_e32 v109, 0xffff0000, v195
	v_lshlrev_b32_e32 v112, 16, v197
	v_and_b32_e32 v113, 0xffff0000, v197
	v_pk_fma_f32 v[104:105], v[104:105], v[136:137], v[108:109]
	v_pk_fma_f32 v[102:103], v[102:103], v[134:135], v[106:107]
	v_pk_fma_f32 v[106:107], v[100:101], v[132:133], v[112:113]
	v_pk_fma_f32 v[100:101], v[98:99], v[130:131], v[110:111]
	v_cvt_pk_bf16_f32 v98, v102, v103
	v_cvt_pk_bf16_f32 v99, v104, v105
	v_cvt_pk_bf16_f32 v100, v100, v101
	v_cvt_pk_bf16_f32 v101, v106, v107
	global_store_dwordx4 v[220:221], v[98:101], off
	v_lshlrev_b32_e32 v102, 16, v200
	v_and_b32_e32 v103, 0xffff0000, v200
	v_lshlrev_b32_e32 v98, 16, v198
	v_and_b32_e32 v99, 0xffff0000, v198
	v_lshlrev_b32_e32 v100, 16, v199
	v_and_b32_e32 v101, 0xffff0000, v199
	v_lshlrev_b32_e32 v104, 16, v201
	v_and_b32_e32 v105, 0xffff0000, v201
	v_pk_fma_f32 v[96:97], v[96:97], v[136:137], v[100:101]
	v_pk_fma_f32 v[94:95], v[94:95], v[134:135], v[98:99]
	v_pk_fma_f32 v[98:99], v[92:93], v[132:133], v[104:105]
; __device__ __forceinline__ float bflo(unsigned u) { return __uint_as_float(u << 16); }
; __device__ __forceinline__ float bfhi(unsigned u) { return __uint_as_float(u & 0xffff0000u); }
; __device__ __forceinline__ void store8(bf16_t* p, const f32x4& a, const f32x4& b) { u32x4 w; w.x = pk2(a[0], a[1]); w.y = pk2(a[2], a[3]); w.z = pk2(b[0], b[1]); w.w = pk2(b[2], b[3]); *(u32x4*)p = w; }
;     __device__ __forceinline__ void operator()(const f32x4 (&acc)[2][2][4][2], const pg8::Unit& u, int wr, int wc, int fr, int fq, int buf) const {
;     ...
;             for (int bj = 0; bj < 2; ++bj) {
;                 const int c0 = u.pn * 256 + bj * 128 + wc * 32 + 8 * fq; const f32x4 g0 = *(const f32x4*)(gt + c0), g1 = *(const f32x4*)(gt + c0 + 4);
;                 if (first) { f32x4 h0[8], h1[8];
; #pragma unroll
;                     for (int q = 0; q < 8; ++q) { const size_t off = (size_t)((q >> 2) * 128 + (q & 3) * 16 + rloc0) * DMODEL + c0; h0[q] = *(const f32x4*)(hi_ + off); h1[q] = *(const f32x4*)(hi_ + off + 4); }
;                     __builtin_amdgcn_sched_barrier(0);
; #pragma unroll
;                     for (int q = 0; q < 8; ++q) { const size_t off = (size_t)((q >> 2) * 128 + (q & 3) * 16 + rloc0) * DMODEL + c0;
;                         store8(HB + off, h0[q] + g0 * acc[q >> 2][bj][q & 3][0], h1[q] + g1 * acc[q >> 2][bj][q & 3][1]); }
;                 } else { u32x4 hw[8];
; #pragma unroll
;                     for (int q = 0; q < 8; ++q) { const size_t off = (size_t)((q >> 2) * 128 + (q & 3) * 16 + rloc0) * DMODEL + c0; hw[q] = *(const u32x4*)(HB + off); }
;                     __builtin_amdgcn_sched_barrier(0);
; #pragma unroll
;                     for (int q = 0; q < 8; ++q) { const size_t off = (size_t)((q >> 2) * 128 + (q & 3) * 16 + rloc0) * DMODEL + c0;
;                         const f32x4 h0 = (f32x4){bflo(hw[q].x), bfhi(hw[q].x), bflo(hw[q].y), bfhi(hw[q].y)}, h1 = (f32x4){bflo(hw[q].z), bfhi(hw[q].z), bflo(hw[q].w), bfhi(hw[q].w)};
;                         store8(HB + off, h0 + g0 * acc[q >> 2][bj][q & 3][0], h1 + g1 * acc[q >> 2][bj][q & 3][1]); }
	v_pk_fma_f32 v[92:93], v[90:91], v[130:131], v[102:103]
	v_cvt_pk_bf16_f32 v90, v94, v95
	v_cvt_pk_bf16_f32 v91, v96, v97
	v_cvt_pk_bf16_f32 v92, v92, v93
	v_cvt_pk_bf16_f32 v93, v98, v99
	global_store_dwordx4 v[222:223], v[90:93], off
	v_lshlrev_b32_e32 v94, 16, v204
	v_and_b32_e32 v95, 0xffff0000, v204
	v_lshlrev_b32_e32 v90, 16, v202
	v_and_b32_e32 v91, 0xffff0000, v202
	v_lshlrev_b32_e32 v92, 16, v203
	v_and_b32_e32 v93, 0xffff0000, v203
	v_lshlrev_b32_e32 v96, 16, v205
	v_and_b32_e32 v97, 0xffff0000, v205
	v_pk_fma_f32 v[88:89], v[88:89], v[136:137], v[92:93]
	v_pk_fma_f32 v[86:87], v[86:87], v[134:135], v[90:91]
	v_pk_fma_f32 v[90:91], v[84:85], v[132:133], v[96:97]
	v_pk_fma_f32 v[84:85], v[82:83], v[130:131], v[94:95]
	v_cvt_pk_bf16_f32 v82, v86, v87
	v_cvt_pk_bf16_f32 v83, v88, v89
	v_cvt_pk_bf16_f32 v84, v84, v85
	v_cvt_pk_bf16_f32 v85, v90, v91
	global_store_dwordx4 v[224:225], v[82:85], off
	v_lshlrev_b32_e32 v86, 16, v208
	v_and_b32_e32 v87, 0xffff0000, v208
	v_lshlrev_b32_e32 v82, 16, v206
	v_and_b32_e32 v83, 0xffff0000, v206
	v_lshlrev_b32_e32 v84, 16, v207
	v_and_b32_e32 v85, 0xffff0000, v207
	v_lshlrev_b32_e32 v88, 16, v209
	v_and_b32_e32 v89, 0xffff0000, v209
	v_pk_fma_f32 v[80:81], v[80:81], v[136:137], v[84:85]
	v_pk_fma_f32 v[78:79], v[78:79], v[134:135], v[82:83]
	v_pk_fma_f32 v[82:83], v[76:77], v[132:133], v[88:89]
	v_pk_fma_f32 v[76:77], v[74:75], v[130:131], v[86:87]
	v_cvt_pk_bf16_f32 v74, v78, v79
	v_cvt_pk_bf16_f32 v75, v80, v81
	v_cvt_pk_bf16_f32 v76, v76, v77
	v_cvt_pk_bf16_f32 v77, v82, v83
	global_store_dwordx4 v[226:227], v[74:77], off
	v_lshlrev_b32_e32 v78, 16, v212
	v_and_b32_e32 v79, 0xffff0000, v212
	v_lshlrev_b32_e32 v74, 16, v210
	v_and_b32_e32 v75, 0xffff0000, v210
	v_lshlrev_b32_e32 v76, 16, v211
	v_and_b32_e32 v77, 0xffff0000, v211
	v_lshlrev_b32_e32 v80, 16, v213
	v_and_b32_e32 v81, 0xffff0000, v213
	v_pk_fma_f32 v[72:73], v[72:73], v[136:137], v[76:77]
	v_pk_fma_f32 v[70:71], v[70:71], v[134:135], v[74:75]
	v_pk_fma_f32 v[74:75], v[64:65], v[132:133], v[80:81]
	v_pk_fma_f32 v[64:65], v[62:63], v[130:131], v[78:79]
	v_cvt_pk_bf16_f32 v62, v70, v71
	v_cvt_pk_bf16_f32 v63, v72, v73
	v_cvt_pk_bf16_f32 v64, v64, v65
	v_cvt_pk_bf16_f32 v65, v74, v75
	global_store_dwordx4 v[174:175], v[62:65], off
	v_add_u32_e32 v74, 0x80, v156
	v_ashrrev_i32_e32 v75, 31, v74
	v_lshl_add_u64 v[74:75], v[74:75], 1, s[4:5]
	v_lshl_add_u64 v[108:109], v[74:75], 0, v[158:159]
	v_lshl_add_u64 v[112:113], v[74:75], 0, v[162:163]
	v_lshl_add_u64 v[116:117], v[74:75], 0, v[166:167]
	v_lshl_add_u64 v[120:121], v[74:75], 0, v[170:171]
	global_load_dwordx4 v[62:65], v[154:155], off offset:528 nt
	global_load_dwordx4 v[70:73], v[154:155], off offset:512 nt
	v_lshl_add_u64 v[110:111], v[74:75], 0, v[160:161]
	global_load_dwordx4 v[76:79], v[108:109], off nt
	global_load_dwordx4 v[80:83], v[110:111], off nt
	v_lshl_add_u64 v[114:115], v[74:75], 0, v[164:165]
	global_load_dwordx4 v[84:87], v[112:113], off nt
	global_load_dwordx4 v[88:91], v[114:115], off nt
	v_lshl_add_u64 v[118:119], v[74:75], 0, v[168:169]
	global_load_dwordx4 v[92:95], v[116:117], off nt
	global_load_dwordx4 v[96:99], v[118:119], off nt
	v_lshl_add_u64 v[74:75], v[74:75], 0, v[172:173]
	global_load_dwordx4 v[100:103], v[120:121], off nt
	global_load_dwordx4 v[104:107], v[74:75], off nt
	s_waitcnt vmcnt(7)
	v_lshlrev_b32_e32 v122, 16, v76
	v_and_b32_e32 v123, 0xffff0000, v76
	v_lshlrev_b32_e32 v76, 16, v77
	v_and_b32_e32 v77, 0xffff0000, v77
	v_lshlrev_b32_e32 v124, 16, v78
	v_and_b32_e32 v125, 0xffff0000, v78
	v_lshlrev_b32_e32 v78, 16, v79
	v_and_b32_e32 v79, 0xffff0000, v79
	v_pk_fma_f32 v[68:69], v[68:69], v[72:73], v[76:77]
	v_pk_fma_f32 v[66:67], v[66:67], v[70:71], v[122:123]
	v_pk_fma_f32 v[76:77], v[60:61], v[64:65], v[78:79]
	v_pk_fma_f32 v[60:61], v[58:59], v[62:63], v[124:125]
	v_cvt_pk_bf16_f32 v58, v66, v67
	v_cvt_pk_bf16_f32 v59, v68, v69
	v_cvt_pk_bf16_f32 v60, v60, v61
	v_cvt_pk_bf16_f32 v61, v76, v77
	global_store_dwordx4 v[108:109], v[58:61], off
	s_waitcnt vmcnt(7)
	v_lshlrev_b32_e32 v66, 16, v82
	v_and_b32_e32 v67, 0xffff0000, v82
	v_lshlrev_b32_e32 v58, 16, v80
	v_and_b32_e32 v59, 0xffff0000, v80
	v_lshlrev_b32_e32 v60, 16, v81
	v_and_b32_e32 v61, 0xffff0000, v81
	v_lshlrev_b32_e32 v68, 16, v83
	v_and_b32_e32 v69, 0xffff0000, v83
	v_pk_fma_f32 v[56:57], v[56:57], v[72:73], v[60:61]
	v_pk_fma_f32 v[54:55], v[54:55], v[70:71], v[58:59]
	v_pk_fma_f32 v[58:59], v[52:53], v[64:65], v[68:69]
	v_pk_fma_f32 v[52:53], v[50:51], v[62:63], v[66:67]
	v_cvt_pk_bf16_f32 v50, v54, v55
	v_cvt_pk_bf16_f32 v51, v56, v57
	v_cvt_pk_bf16_f32 v52, v52, v53
	v_cvt_pk_bf16_f32 v53, v58, v59
	global_store_dwordx4 v[110:111], v[50:53], off
	s_waitcnt vmcnt(7)
; __device__ __forceinline__ float bflo(unsigned u) { return __uint_as_float(u << 16); }
; __device__ __forceinline__ float bfhi(unsigned u) { return __uint_as_float(u & 0xffff0000u); }
; __device__ __forceinline__ void store8(bf16_t* p, const f32x4& a, const f32x4& b) { u32x4 w; w.x = pk2(a[0], a[1]); w.y = pk2(a[2], a[3]); w.z = pk2(b[0], b[1]); w.w = pk2(b[2], b[3]); *(u32x4*)p = w; }
; #define PG8_BAR __builtin_amdgcn_s_barrier()
; #define PG8_FLAG(v) do { } while (0)
; template <class Epi, class Sched, bool APERM, bool ABLK = false, bool RELAX = true>
; __device__ __forceinline__ void gemm_phase(LAS unsigned char* lds, const Gemm g, const Sched& S, const Epi& E) {
;     ...
;         if (!has_next) break;
;         PG8_FLAG(1u);
; #pragma unroll
;         for (int a = 0; a < 2; ++a)
; #pragma unroll
;             for (int b = 0; b < 2; ++b)
; #pragma unroll
;                 for (int m = 0; m < 4; ++m)
; #pragma unroll
;                     for (int n = 0; n < 2; ++n) acc[a][b][m][n] = (f32x4){0.f, 0.f, 0.f, 0.f};
;         cur = nxt; cA = nA; cB = nB; ++ui;
;         if (wr == 1) PG8_BAR;
;     __device__ __forceinline__ void operator()(const f32x4 (&acc)[2][2][4][2], const pg8::Unit& u, int wr, int wc, int fr, int fq, int buf) const {
;     ...
;                     for (int q = 0; q < 8; ++q) { const size_t off = (size_t)((q >> 2) * 128 + (q & 3) * 16 + rloc0) * DMODEL + c0;
;                         store8(HB + off, h0[q] + g0 * acc[q >> 2][bj][q & 3][0], h1[q] + g1 * acc[q >> 2][bj][q & 3][1]); }
;                 } else { u32x4 hw[8];
; #pragma unroll
;                     for (int q = 0; q < 8; ++q) { const size_t off = (size_t)((q >> 2) * 128 + (q & 3) * 16 + rloc0) * DMODEL + c0; hw[q] = *(const u32x4*)(HB + off); }
;                     __builtin_amdgcn_sched_barrier(0);
; #pragma unroll
;                     for (int q = 0; q < 8; ++q) { const size_t off = (size_t)((q >> 2) * 128 + (q & 3) * 16 + rloc0) * DMODEL + c0;
;                         const f32x4 h0 = (f32x4){bflo(hw[q].x), bfhi(hw[q].x), bflo(hw[q].y), bfhi(hw[q].y)}, h1 = (f32x4){bflo(hw[q].z), bfhi(hw[q].z), bflo(hw[q].w), bfhi(hw[q].w)};
;                         store8(HB + off, h0 + g0 * acc[q >> 2][bj][q & 3][0], h1 + g1 * acc[q >> 2][bj][q & 3][1]); }
	v_lshlrev_b32_e32 v54, 16, v86
	v_and_b32_e32 v55, 0xffff0000, v86
	v_lshlrev_b32_e32 v50, 16, v84
	v_and_b32_e32 v51, 0xffff0000, v84
	v_lshlrev_b32_e32 v52, 16, v85
	v_and_b32_e32 v53, 0xffff0000, v85
	v_lshlrev_b32_e32 v56, 16, v87
	v_and_b32_e32 v57, 0xffff0000, v87
	v_pk_fma_f32 v[48:49], v[48:49], v[72:73], v[52:53]
	v_pk_fma_f32 v[46:47], v[46:47], v[70:71], v[50:51]
	v_pk_fma_f32 v[50:51], v[44:45], v[64:65], v[56:57]
	v_pk_fma_f32 v[44:45], v[42:43], v[62:63], v[54:55]
	v_cvt_pk_bf16_f32 v42, v46, v47
	v_cvt_pk_bf16_f32 v43, v48, v49
	v_cvt_pk_bf16_f32 v44, v44, v45
	v_cvt_pk_bf16_f32 v45, v50, v51
	global_store_dwordx4 v[112:113], v[42:45], off
	s_waitcnt vmcnt(7)
	v_lshlrev_b32_e32 v46, 16, v90
	v_and_b32_e32 v47, 0xffff0000, v90
	v_lshlrev_b32_e32 v42, 16, v88
	v_and_b32_e32 v43, 0xffff0000, v88
	v_lshlrev_b32_e32 v44, 16, v89
	v_and_b32_e32 v45, 0xffff0000, v89
	v_lshlrev_b32_e32 v48, 16, v91
	v_and_b32_e32 v49, 0xffff0000, v91
	v_pk_fma_f32 v[40:41], v[40:41], v[72:73], v[44:45]
	v_pk_fma_f32 v[38:39], v[38:39], v[70:71], v[42:43]
	v_pk_fma_f32 v[42:43], v[36:37], v[64:65], v[48:49]
	v_pk_fma_f32 v[36:37], v[34:35], v[62:63], v[46:47]
	v_cvt_pk_bf16_f32 v34, v38, v39
	v_cvt_pk_bf16_f32 v35, v40, v41
	v_cvt_pk_bf16_f32 v36, v36, v37
	v_cvt_pk_bf16_f32 v37, v42, v43
	global_store_dwordx4 v[114:115], v[34:37], off
	s_waitcnt vmcnt(7)
	v_lshlrev_b32_e32 v38, 16, v94
	v_and_b32_e32 v39, 0xffff0000, v94
	v_lshlrev_b32_e32 v34, 16, v92
	v_and_b32_e32 v35, 0xffff0000, v92
	v_lshlrev_b32_e32 v36, 16, v93
	v_and_b32_e32 v37, 0xffff0000, v93
	v_lshlrev_b32_e32 v40, 16, v95
	v_and_b32_e32 v41, 0xffff0000, v95
	v_pk_fma_f32 v[32:33], v[32:33], v[72:73], v[36:37]
	v_pk_fma_f32 v[30:31], v[30:31], v[70:71], v[34:35]
	v_pk_fma_f32 v[34:35], v[28:29], v[64:65], v[40:41]
	v_pk_fma_f32 v[28:29], v[26:27], v[62:63], v[38:39]
	v_cvt_pk_bf16_f32 v26, v30, v31
	v_cvt_pk_bf16_f32 v27, v32, v33
	v_cvt_pk_bf16_f32 v28, v28, v29
	v_cvt_pk_bf16_f32 v29, v34, v35
	global_store_dwordx4 v[116:117], v[26:29], off
	s_waitcnt vmcnt(7)
	v_lshlrev_b32_e32 v30, 16, v98
	v_and_b32_e32 v31, 0xffff0000, v98
	v_lshlrev_b32_e32 v26, 16, v96
	v_and_b32_e32 v27, 0xffff0000, v96
	v_lshlrev_b32_e32 v28, 16, v97
	v_and_b32_e32 v29, 0xffff0000, v97
	v_lshlrev_b32_e32 v32, 16, v99
	v_and_b32_e32 v33, 0xffff0000, v99
	v_pk_fma_f32 v[24:25], v[24:25], v[72:73], v[28:29]
	v_pk_fma_f32 v[22:23], v[22:23], v[70:71], v[26:27]
	v_pk_fma_f32 v[26:27], v[20:21], v[64:65], v[32:33]
	v_pk_fma_f32 v[20:21], v[18:19], v[62:63], v[30:31]
	v_cvt_pk_bf16_f32 v18, v22, v23
	v_cvt_pk_bf16_f32 v19, v24, v25
	v_cvt_pk_bf16_f32 v20, v20, v21
	v_cvt_pk_bf16_f32 v21, v26, v27
	global_store_dwordx4 v[118:119], v[18:21], off
	s_waitcnt vmcnt(7)
	v_lshlrev_b32_e32 v22, 16, v102
	v_and_b32_e32 v23, 0xffff0000, v102
	v_lshlrev_b32_e32 v18, 16, v100
	v_and_b32_e32 v19, 0xffff0000, v100
	v_lshlrev_b32_e32 v20, 16, v101
	v_and_b32_e32 v21, 0xffff0000, v101
	v_lshlrev_b32_e32 v24, 16, v103
	v_and_b32_e32 v25, 0xffff0000, v103
	v_pk_fma_f32 v[16:17], v[16:17], v[72:73], v[20:21]
	v_pk_fma_f32 v[14:15], v[14:15], v[70:71], v[18:19]
	v_pk_fma_f32 v[18:19], v[12:13], v[64:65], v[24:25]
	v_pk_fma_f32 v[12:13], v[10:11], v[62:63], v[22:23]
	v_cvt_pk_bf16_f32 v10, v14, v15
	v_cvt_pk_bf16_f32 v11, v16, v17
	v_cvt_pk_bf16_f32 v12, v12, v13
	v_cvt_pk_bf16_f32 v13, v18, v19
	global_store_dwordx4 v[120:121], v[10:13], off
	s_waitcnt vmcnt(7)
	v_lshlrev_b32_e32 v14, 16, v106
	v_and_b32_e32 v15, 0xffff0000, v106
	v_lshlrev_b32_e32 v10, 16, v104
	v_and_b32_e32 v11, 0xffff0000, v104
	v_lshlrev_b32_e32 v12, 16, v105
	v_and_b32_e32 v13, 0xffff0000, v105
	v_lshlrev_b32_e32 v16, 16, v107
	v_and_b32_e32 v17, 0xffff0000, v107
	v_pk_fma_f32 v[8:9], v[8:9], v[72:73], v[12:13]
	v_pk_fma_f32 v[6:7], v[6:7], v[70:71], v[10:11]
	v_pk_fma_f32 v[10:11], v[4:5], v[64:65], v[16:17]
	v_pk_fma_f32 v[4:5], v[2:3], v[62:63], v[14:15]
	v_cvt_pk_bf16_f32 v2, v6, v7
	v_cvt_pk_bf16_f32 v3, v8, v9
	v_cvt_pk_bf16_f32 v4, v4, v5
	v_cvt_pk_bf16_f32 v5, v10, v11
	global_store_dwordx4 v[74:75], v[2:5], off
	s_and_b64 vcc, exec, s[0:1]
	s_mov_b64 s[0:1], -1
	s_cbranch_vccnz .LBB0_2328
	s_andn2_b64 vcc, exec, s[6:7]
	s_cbranch_vccnz .LBB0_2327
	s_barrier
	s_branch .LBB0_2327
